# DFT phases: twiddle-matrix fragment loads hoisted above the staging barrier and kept in registers across the 4 same-type items (loaded once per variant run); retention-state K loads issued in the init
# speedup vs baseline: 1.0106x; 1.0077x over previous
; __device__ __forceinline__ float log_sigmoid(float x) { return fminf(x, 0.f) - log1pf(expf(-fabsf(x))); }
; template <int STAGE>
; __device__ void dft_phase(const bf16_t* src, bf16_t* dst, const bf16_t* DT, LAS unsigned char* lds) {
;   for (int it = blockIdx.x; it < 2048; it += gridDim.x) {
; __global__ void __launch_bounds__(512, 2) mega(Params p) {
;     ...
;     float lgf2[4], lgb2[4], lgf[4], lgb[4];
; #pragma unroll
;     for (int hh = 0; hh < 4; ++hh) { lgf[hh] = log_sigmoid(p.in[10][layer * 4 + hh]); lgb[hh] = log_sigmoid(p.in[11][layer * 4 + hh]);
;       lgf2[hh] = lgf[hh] * 1.4426950408889634f; lgb2[hh] = lgb[hh] * 1.4426950408889634f; }
.LBB0_427:
	s_or_b64 exec, exec, s[22:23]
	v_readlane_b32 s6, v255, 56
	v_readlane_b32 s7, v255, 57
	s_lshl_b32 s20, s6, 2
	v_readlane_b32 s60, v250, 17
	s_lshl_b64 s[6:7], s[20:21], 2
	v_readlane_b32 s64, v250, 21
	v_readlane_b32 s65, v250, 22
	s_add_u32 s12, s64, s6
	v_readlane_b32 s66, v250, 23
	s_addc_u32 s13, s65, s7
	v_readlane_b32 s67, v250, 24
	s_add_u32 s6, s66, s6
	s_addc_u32 s7, s67, s7
	s_waitcnt lgkmcnt(0)
	s_barrier
	global_load_dwordx4 v[52:55], v161, s[12:13]
	global_load_dwordx4 v[48:51], v161, s[6:7]
	v_readlane_b32 s6, v252, 31
	v_readlane_b32 s61, v250, 18
	v_readlane_b32 s7, v252, 32
	v_readlane_b32 s62, v250, 19
	v_readlane_b32 s60, v255, 50
	v_cndmask_b32_e64 v0, 0, 1, s[6:7]
	v_readlane_b32 s66, v255, 53
	v_cmp_ne_u32_e64 s[64:65], 1, v0
	s_andn2_b64 vcc, exec, s[6:7]
	v_readlane_b32 s6, v255, 32
	v_readlane_b32 s7, v255, 30
	v_readlane_b32 s12, v255, 28
	s_mov_b32 s13, s2
	v_readlane_b32 s61, v255, 51
	v_readlane_b32 s52, v255, 55
	v_readlane_b32 s62, v255, 52
	v_readlane_b32 s67, v255, 54
	v_readlane_b32 s63, v250, 20
	v_readlane_b32 s68, v250, 25
	v_readlane_b32 s69, v250, 26
	v_readlane_b32 s70, v250, 27
	v_readlane_b32 s71, v250, 28
	v_readlane_b32 s72, v250, 29
	v_readlane_b32 s73, v250, 30
	v_readlane_b32 s74, v250, 31
	v_readlane_b32 s75, v250, 32
	s_mov_b32 s70, 0
	s_cbranch_vccz .LBB0_433

; #define LAS __attribute__((address_space(3)))
; __device__ __forceinline__ f32x16 mfma32(bf16x8 a, bf16x8 b, f32x16 c) { return __builtin_amdgcn_mfma_f32_32x32x16_bf16(a, b, c, 0, 0, 0); }
; template <int STAGE>
; __device__ void dft_item(const bf16_t* __restrict__ src, bf16_t* __restrict__ dst, const bf16_t* __restrict__ Ct, const bf16_t* __restrict__ St,
;                          int N, int lgN, int rowbase, int j, int chblk, int S, int N1, int N2, LAS unsigned char* lds) {
;     ...
; #pragma unroll
;   for (int it = 0; it < 4; ++it) {
;     const int q = tid + it * 512, n = q >> lgcpr, cq = q & (cpr - 1), part = cq >> (lgcpr - 1), cc = cq & ((cpr >> 1) - 1);
;     const int irow = STAGE == 1 ? rowbase + N2 * n + j : rowbase + j * N2 + n;
;     const u32x4 v = *(const u32x4*)(src + (size_t)irow * 1024 + part * 512 + chblk * CB + cc * 8);
;     *(LAS u32x4*)(lds + n * stride + (part * CB + cc * 8) * 2) = v;
;   }
;   __syncthreads();
;   const int kts = N >> 5, kt = w & (kts - 1), chsub = w >> (lgN - 5);
;   const int i16 = l & 15, q4 = i16 >> 2, p4 = i16 & 3, G1 = (l >> 4) & 1, h = l >> 5;
;   const unsigned colre = (unsigned)(chsub * 32 + 16 * G1 + 4 * p4) * 2u, colim = colre + (unsigned)CB * 2u;
;   const int kout = kt * 32 + (l & 31);
;   f32x16 a0 = {}, a1 = {}, a2 = {};
;   const int nks = N >> 4;
;   bf16x8 Bc[8], Bs[8];
; #pragma unroll
;   for (int ks = 0; ks < 8; ++ks) if (ks < nks) { Bc[ks] = *(const bf16x8*)(Ct + kout * N + 16 * ks + 8 * h); Bs[ks] = *(const bf16x8*)(St + kout * N + 16 * ks + 8 * h); }
; #pragma unroll
;   for (int ks = 0; ks < 8; ++ks) if (ks < nks) {
;     const unsigned rlo = (unsigned)(16 * ks + 8 * h + q4) * stride, rhi = rlo + 4u * stride;
;     const bf16x8 Ar = tr_frag(lds, rlo + colre, rhi + colre), Ai = tr_frag(lds, rlo + colim, rhi + colim);
;     a0 = mfma32(Ar, Bc[ks], a0); a0 = mfma32(Ai, Bs[ks], a0);
;     if (STAGE == 1) { a1 = mfma32(Ai, Bc[ks], a1); a2 = mfma32(Ar, Bs[ks], a2); }
;   }
.LBB0_433:
	s_cmpk_gt_i32 s13, 0x3ff
	s_mov_b64 s[22:23], -1
	s_cbranch_scc0 .LBB0_435
	s_and_b32 s20, s12, 0x7ffff800
	s_bfe_u32 s34, s13, 0x60001
	s_or_b32 s23, s20, s34
	v_mov_b32_e32 v6, v214
	s_addk_i32 s23, 0xc000
	v_and_b32_e32 v0, 0xffffffc0, v6
	v_add_u32_e32 v0, s23, v0
	v_ashrrev_i32_e32 v1, 31, v0
	v_lshlrev_b32_e32 v2, 4, v6
	v_lshlrev_b64 v[0:1], 11, v[0:1]
	v_and_b32_e32 v8, 0x200, v2
	s_and_b32 s22, s7, 0x100
	v_lshl_add_u64 v[0:1], s[4:5], 0, v[0:1]
	v_lshlrev_b32_e32 v160, 1, v8
	v_lshl_add_u64 v[0:1], v[0:1], 0, v[160:161]
	s_lshl_b32 s20, s22, 1
	v_lshl_add_u64 v[0:1], v[0:1], 0, s[20:21]
	v_and_b32_e32 v4, 0x1f0, v2
	v_mov_b32_e32 v5, v161
	v_lshl_add_u64 v[0:1], v[0:1], 0, v[4:5]
	global_load_dwordx4 v[12:15], v[0:1], off
	v_ashrrev_i32_e32 v7, 6, v6
	s_movk_i32 s35, 0x440
	v_mul_lo_u32 v9, v7, s35
	v_add_u32_e32 v9, 0, v9
	v_add3_u32 v9, v9, v8, v4
	v_and_b32_e32 v59, 31, v6
	v_readlane_b32 s36, v252, 33
	v_lshlrev_b32_e32 v58, 5, v7
	v_readlane_b32 s37, v252, 34
	v_mov_b32_e32 v57, v161
	v_mov_b32_e32 v28, v9
	v_add_u32_e32 v0, 0x200, v6
	v_lshrrev_b32_e32 v9, 6, v0
	v_and_b32_e32 v0, 0xffffffc0, v0
	v_add_u32_e32 v0, s23, v0
	v_ashrrev_i32_e32 v1, 31, v0
	v_lshlrev_b64 v[0:1], 11, v[0:1]
	v_lshl_add_u64 v[0:1], s[4:5], 0, v[0:1]
	v_lshl_add_u64 v[0:1], v[0:1], 0, v[160:161]
	v_lshl_add_u64 v[0:1], v[0:1], 0, s[20:21]
	v_lshl_add_u64 v[0:1], v[0:1], 0, v[4:5]
	global_load_dwordx4 v[16:19], v[0:1], off
	v_mul_lo_u32 v9, v9, s35
	v_add_u32_e32 v9, 0, v9
	v_add3_u32 v9, v9, v8, v4
	v_mov_b32_e32 v29, v9
	v_add_u32_e32 v0, 0x400, v6
	v_lshrrev_b32_e32 v9, 6, v0
	v_and_b32_e32 v0, 0xffffffc0, v0
	v_add_u32_e32 v0, s23, v0
	v_ashrrev_i32_e32 v1, 31, v0
	v_lshlrev_b64 v[0:1], 11, v[0:1]
	v_lshl_add_u64 v[0:1], s[4:5], 0, v[0:1]
	v_lshl_add_u64 v[0:1], v[0:1], 0, v[160:161]
	v_lshl_add_u64 v[0:1], v[0:1], 0, s[20:21]
	v_lshl_add_u64 v[0:1], v[0:1], 0, v[4:5]
	global_load_dwordx4 v[20:23], v[0:1], off
	v_mul_lo_u32 v9, v9, s35
	v_add_u32_e32 v9, 0, v9
	v_add3_u32 v9, v9, v8, v4
	v_mov_b32_e32 v30, v9
	v_add_u32_e32 v0, 0x600, v6
	v_lshrrev_b32_e32 v9, 6, v0
	v_and_b32_e32 v0, 0xffffffc0, v0
	v_add_u32_e32 v0, s23, v0
	v_ashrrev_i32_e32 v1, 31, v0
	v_lshlrev_b64 v[0:1], 11, v[0:1]
	v_lshl_add_u64 v[0:1], s[4:5], 0, v[0:1]
	v_lshl_add_u64 v[0:1], v[0:1], 0, v[160:161]
	v_lshl_add_u64 v[0:1], v[0:1], 0, s[20:21]
	v_lshl_add_u64 v[0:1], v[0:1], 0, v[4:5]
	global_load_dwordx4 v[24:27], v[0:1], off
	v_mul_lo_u32 v5, v9, s35
	v_add_u32_e32 v5, 0, v5
	v_add3_u32 v4, v5, v8, v4
	v_lshlrev_b32_e32 v160, 6, v59
	v_mul_u32_u24_e32 v59, s34, v59
	v_cvt_f32_u32_e32 v59, v59
	v_mul_f32_e32 v59, 0x3a000000, v59
	v_mov_b32_e32 v31, v4
	v_lshlrev_b32_e32 v1, 2, v6
	v_and_b32_e32 v0, 16, v6
	v_and_b32_e32 v1, 12, v1
	v_or3_b32 v5, v0, v1, v58
	v_lshl_add_u64 v[0:1], s[36:37], 0, v[160:161]
	v_lshrrev_b32_e32 v2, 1, v6
	v_readlane_b32 s36, v252, 35
	v_and_b32_e32 v56, 16, v2
	v_readlane_b32 s37, v252, 36
	v_lshl_add_u64 v[0:1], v[0:1], 0, v[56:57]
	v_lshl_add_u64 v[2:3], s[36:37], 0, v[160:161]
	v_lshl_add_u64 v[2:3], v[2:3], 0, v[56:57]
	s_cmp_eq_u32 s70, 2
	s_cbranch_scc1 .Ld1skip_2
	global_load_dwordx4 v[126:129], v[0:1], off
	global_load_dwordx4 v[130:133], v[2:3], off
	global_load_dwordx4 v[134:137], v[0:1], off offset:32
	global_load_dwordx4 v[138:141], v[2:3], off offset:32
	s_mov_b32 s70, 2
	s_waitcnt vmcnt(7)
	ds_write_b128 v28, v[12:15]
	s_waitcnt vmcnt(6)
	ds_write_b128 v29, v[16:19]
	s_waitcnt vmcnt(5)
	ds_write_b128 v30, v[20:23]
	s_waitcnt vmcnt(4)
	ds_write_b128 v31, v[24:27]
	s_branch .Ld1join_2
.Ld1skip_2:
	s_waitcnt vmcnt(3)
	ds_write_b128 v28, v[12:15]
	s_waitcnt vmcnt(2)
	ds_write_b128 v29, v[16:19]
	s_waitcnt vmcnt(1)
	ds_write_b128 v30, v[20:23]
	s_waitcnt vmcnt(0)
	ds_write_b128 v31, v[24:27]
.Ld1join_2:
	s_waitcnt lgkmcnt(0)
	s_barrier
	v_lshrrev_b32_e32 v4, 2, v6
	v_and_b32_e32 v1, 11, v4
	v_lshlrev_b32_e32 v0, 1, v5
	v_mul_u32_u24_e32 v1, 0x440, v1
	v_add3_u32 v74, 0, v0, v1
	ds_read_b64_tr_b16 v[36:37], v74
	ds_read_b64_tr_b16 v[38:39], v74 offset:4352
	ds_read_b64_tr_b16 v[20:21], v74 offset:512
	ds_read_b64_tr_b16 v[22:23], v74 offset:4864
	ds_read_b64_tr_b16 v[68:69], v74 offset:17408
	ds_read_b64_tr_b16 v[70:71], v74 offset:21760
	ds_read_b64_tr_b16 v[72:73], v74 offset:17920
	ds_read_b64_tr_b16 v[74:75], v74 offset:22272
	v_or_b32_e32 v160, s23, v160
	s_waitcnt vmcnt(3) lgkmcnt(6)
	v_mfma_f32_32x32x16_bf16 v[0:15], v[36:39], v[126:129], 0
	s_waitcnt vmcnt(2) lgkmcnt(4)
	v_mfma_f32_32x32x16_bf16 v[0:15], v[20:23], v[130:133], v[0:15]
	v_mfma_f32_32x32x16_bf16 v[16:31], v[20:23], v[126:129], 0
	v_mfma_f32_32x32x16_bf16 v[32:47], v[36:39], v[130:133], 0
	s_waitcnt vmcnt(1) lgkmcnt(2)
	v_mfma_f32_32x32x16_bf16 v[0:15], v[68:71], v[134:137], v[0:15]
	s_waitcnt vmcnt(0) lgkmcnt(0)
; __device__ __forceinline__ f32x16 mfma32(bf16x8 a, bf16x8 b, f32x16 c) { return __builtin_amdgcn_mfma_f32_32x32x16_bf16(a, b, c, 0, 0, 0); }
; template <int STAGE>
; __device__ void dft_item(const bf16_t* __restrict__ src, bf16_t* __restrict__ dst, const bf16_t* __restrict__ Ct, const bf16_t* __restrict__ St,
;                          int N, int lgN, int rowbase, int j, int chblk, int S, int N1, int N2, LAS unsigned char* lds) {
;     ...
;     a0 = mfma32(Ar, Bc[ks], a0); a0 = mfma32(Ai, Bs[ks], a0);
;     if (STAGE == 1) { a1 = mfma32(Ai, Bc[ks], a1); a2 = mfma32(Ar, Bs[ks], a2); }
;   }
;   const int chb = chblk * CB + chsub * 32;
;   if (STAGE == 1) {
;     const int mm = (j * kout) & (S - 1); const float fr = (float)mm / (float)S;
;     const float c = __builtin_amdgcn_cosf(fr), s = __builtin_amdgcn_sinf(fr);
;     const size_t orow = (size_t)(rowbase + kout * N2 + j) * 1024;
;     f32x16 re, im;
; #pragma unroll
;     for (int i = 0; i < 16; ++i) { const float yr = a0[i], yi = a1[i] - a2[i]; re[i] = yr * c + yi * s; im[i] = yi * c - yr * s; }
;     store_tile16(dst + orow + chb, re, 1.f, h); store_tile16(dst + orow + 512 + chb, im, 1.f, h);
;   } else {
;     const size_t orow = (size_t)(rowbase + j + N1 * kout) * 512;
;     store_tile16(dst + orow + chb, a0, 1.f, h);
;   }
;   __syncthreads();
	v_mfma_f32_32x32x16_bf16 v[0:15], v[72:75], v[138:141], v[0:15]
	v_mfma_f32_32x32x16_bf16 v[16:31], v[72:75], v[134:137], v[16:31]
	v_sin_f32_e32 v62, v59
	v_cos_f32_e32 v60, v59
	v_mfma_f32_32x32x16_bf16 v[32:47], v[68:71], v[138:141], v[32:47]
	s_nop 11
	v_sub_f32_e32 v47, v31, v47
	v_sub_f32_e32 v46, v30, v46
	v_sub_f32_e32 v31, v23, v39
	v_sub_f32_e32 v30, v22, v38
	v_sub_f32_e32 v23, v21, v37
	v_sub_f32_e32 v22, v20, v36
	v_sub_f32_e32 v21, v19, v35
	v_sub_f32_e32 v20, v18, v34
	v_sub_f32_e32 v19, v17, v33
	v_sub_f32_e32 v18, v16, v32
	v_pk_mul_f32 v[16:17], v[62:63], v[0:1] op_sel_hi:[0,1]
	v_pk_fma_f32 v[16:17], v[60:61], v[18:19], v[16:17] op_sel_hi:[0,1,1] neg_lo:[0,0,1] neg_hi:[0,0,1]
	v_pk_mul_f32 v[18:19], v[62:63], v[18:19] op_sel_hi:[0,1]
	v_sub_f32_e32 v41, v25, v41
	v_sub_f32_e32 v40, v24, v40
	v_pk_fma_f32 v[24:25], v[60:61], v[0:1], v[18:19] op_sel_hi:[0,1,1]
	v_pk_mul_f32 v[0:1], v[62:63], v[2:3] op_sel_hi:[0,1]
	v_pk_fma_f32 v[18:19], v[60:61], v[20:21], v[0:1] op_sel_hi:[0,1,1] neg_lo:[0,0,1] neg_hi:[0,0,1]
	v_pk_mul_f32 v[0:1], v[62:63], v[20:21] op_sel_hi:[0,1]
	v_sub_f32_e32 v43, v27, v43
	v_sub_f32_e32 v42, v26, v42
	v_pk_fma_f32 v[26:27], v[60:61], v[2:3], v[0:1] op_sel_hi:[0,1,1]
	v_pk_mul_f32 v[0:1], v[62:63], v[4:5] op_sel_hi:[0,1]
	v_pk_fma_f32 v[20:21], v[60:61], v[22:23], v[0:1] op_sel_hi:[0,1,1] neg_lo:[0,0,1] neg_hi:[0,0,1]
	v_pk_mul_f32 v[0:1], v[62:63], v[22:23] op_sel_hi:[0,1]
	v_sub_f32_e32 v45, v29, v45
	v_sub_f32_e32 v44, v28, v44
	v_pk_fma_f32 v[28:29], v[60:61], v[4:5], v[0:1] op_sel_hi:[0,1,1]
	v_pk_mul_f32 v[0:1], v[62:63], v[6:7] op_sel_hi:[0,1]
	v_pk_fma_f32 v[22:23], v[60:61], v[30:31], v[0:1] op_sel_hi:[0,1,1] neg_lo:[0,0,1] neg_hi:[0,0,1]
	v_pk_mul_f32 v[0:1], v[62:63], v[30:31] op_sel_hi:[0,1]
	v_pk_fma_f32 v[30:31], v[60:61], v[6:7], v[0:1] op_sel_hi:[0,1,1]
	v_pk_mul_f32 v[2:3], v[62:63], v[40:41] op_sel_hi:[0,1]
	v_pk_mul_f32 v[4:5], v[62:63], v[42:43] op_sel_hi:[0,1]
	v_pk_mul_f32 v[6:7], v[62:63], v[44:45] op_sel_hi:[0,1]
	v_pk_mul_f32 v[32:33], v[62:63], v[46:47] op_sel_hi:[0,1]
	v_pk_mul_f32 v[0:1], v[62:63], v[8:9] op_sel_hi:[0,1]
	v_pk_fma_f32 v[8:9], v[60:61], v[8:9], v[2:3] op_sel_hi:[0,1,1]
	v_pk_mul_f32 v[2:3], v[62:63], v[10:11] op_sel_hi:[0,1]
	v_pk_fma_f32 v[10:11], v[60:61], v[10:11], v[4:5] op_sel_hi:[0,1,1]
	v_pk_mul_f32 v[4:5], v[62:63], v[12:13] op_sel_hi:[0,1]
	v_pk_fma_f32 v[12:13], v[60:61], v[12:13], v[6:7] op_sel_hi:[0,1,1]
	v_pk_mul_f32 v[6:7], v[62:63], v[14:15] op_sel_hi:[0,1]
	v_pk_fma_f32 v[14:15], v[60:61], v[14:15], v[32:33] op_sel_hi:[0,1,1]
	v_add_u32_e32 v32, s22, v58
	v_lshlrev_b64 v[34:35], 11, v[160:161]
	v_lshl_add_u64 v[34:35], s[10:11], 0, v[34:35]
	v_ashrrev_i32_e32 v33, 31, v32
	v_lshl_add_u64 v[32:33], v[32:33], 1, v[34:35]
	v_cvt_pk_bf16_f32 v8, v8, v9
	v_cvt_pk_bf16_f32 v9, v10, v11
	v_cvt_pk_bf16_f32 v10, v12, v13
	v_cvt_pk_bf16_f32 v11, v14, v15
	v_pk_fma_f32 v[0:1], v[60:61], v[40:41], v[0:1] op_sel_hi:[0,1,1] neg_lo:[0,0,1] neg_hi:[0,0,1]
	v_pk_fma_f32 v[2:3], v[60:61], v[42:43], v[2:3] op_sel_hi:[0,1,1] neg_lo:[0,0,1] neg_hi:[0,0,1]
	v_pk_fma_f32 v[4:5], v[60:61], v[44:45], v[4:5] op_sel_hi:[0,1,1] neg_lo:[0,0,1] neg_hi:[0,0,1]
	v_pk_fma_f32 v[6:7], v[60:61], v[46:47], v[6:7] op_sel_hi:[0,1,1] neg_lo:[0,0,1] neg_hi:[0,0,1]
	v_lshl_add_u64 v[32:33], v[32:33], 0, v[56:57]
	v_permlane32_swap_b32_e32 v8, v10
	v_permlane32_swap_b32_e32 v9, v11
	v_cvt_pk_bf16_f32 v24, v24, v25
	v_cvt_pk_bf16_f32 v25, v26, v27
	v_cvt_pk_bf16_f32 v26, v28, v29
	v_cvt_pk_bf16_f32 v27, v30, v31
	global_store_dwordx4 v[32:33], v[8:11], off offset:32
	v_cvt_pk_bf16_f32 v0, v0, v1
	v_cvt_pk_bf16_f32 v1, v2, v3
	v_cvt_pk_bf16_f32 v8, v16, v17
	v_cvt_pk_bf16_f32 v9, v18, v19
	v_cvt_pk_bf16_f32 v10, v20, v21
	v_cvt_pk_bf16_f32 v11, v22, v23
	v_cvt_pk_bf16_f32 v2, v4, v5
	v_cvt_pk_bf16_f32 v3, v6, v7
	v_permlane32_swap_b32_e32 v24, v26
	v_permlane32_swap_b32_e32 v25, v27
	v_permlane32_swap_b32_e32 v8, v10
	v_permlane32_swap_b32_e32 v9, v11
	v_permlane32_swap_b32_e32 v0, v2
	v_permlane32_swap_b32_e32 v1, v3
	global_store_dwordx4 v[32:33], v[24:27], off
	global_store_dwordx4 v[32:33], v[8:11], off offset:1024
	global_store_dwordx4 v[32:33], v[0:3], off offset:1056
	s_barrier
	s_mov_b64 s[22:23], 0
; #define LAS __attribute__((address_space(3)))
; template <int STAGE>
; __device__ void dft_item(const bf16_t* __restrict__ src, bf16_t* __restrict__ dst, const bf16_t* __restrict__ Ct, const bf16_t* __restrict__ St,
;                          int N, int lgN, int rowbase, int j, int chblk, int S, int N1, int N2, LAS unsigned char* lds) {
;     ...
; #pragma unroll
;   for (int it = 0; it < 4; ++it) {
;     const int q = tid + it * 512, n = q >> lgcpr, cq = q & (cpr - 1), part = cq >> (lgcpr - 1), cc = cq & ((cpr >> 1) - 1);
;     const int irow = STAGE == 1 ? rowbase + N2 * n + j : rowbase + j * N2 + n;
;     const u32x4 v = *(const u32x4*)(src + (size_t)irow * 1024 + part * 512 + chblk * CB + cc * 8);
;     *(LAS u32x4*)(lds + n * stride + (part * CB + cc * 8) * 2) = v;
;   }
;   __syncthreads();
;   const int kts = N >> 5, kt = w & (kts - 1), chsub = w >> (lgN - 5);
;   const int i16 = l & 15, q4 = i16 >> 2, p4 = i16 & 3, G1 = (l >> 4) & 1, h = l >> 5;
;   const unsigned colre = (unsigned)(chsub * 32 + 16 * G1 + 4 * p4) * 2u, colim = colre + (unsigned)CB * 2u;
;   const int kout = kt * 32 + (l & 31);
;   f32x16 a0 = {}, a1 = {}, a2 = {};
;   const int nks = N >> 4;
;   bf16x8 Bc[8], Bs[8];
; #pragma unroll
;   for (int ks = 0; ks < 8; ++ks) if (ks < nks) { Bc[ks] = *(const bf16x8*)(Ct + kout * N + 16 * ks + 8 * h); Bs[ks] = *(const bf16x8*)(St + kout * N + 16 * ks + 8 * h); }
; template <int STAGE>
; __device__ void dft_phase(const bf16_t* src, bf16_t* dst, const bf16_t* DT, LAS unsigned char* lds) {
;     ...
;     if (it < 1024) dft_item<STAGE>(src, dst, DT + DT_C128, DT + DT_S128, 128, 7, 16384, it >> 3, it & 7, 16384, 128, 128, lds);
.LBB0_435:
	s_andn2_b64 vcc, exec, s[22:23]
	s_cbranch_vccnz .LBB0_432
	s_ashr_i32 s34, s13, 3
	v_mov_b32_e32 v6, v214
	s_add_i32 s23, s34, 0x4000
	v_ashrrev_i32_e32 v7, 4, v6
	v_lshl_add_u32 v0, v7, 7, s23
	v_ashrrev_i32_e32 v1, 31, v0
	v_bfe_u32 v8, v6, 3, 1
	v_lshlrev_b64 v[0:1], 11, v[0:1]
	s_and_b32 s22, s6, 0x1c0
	v_lshl_add_u64 v[0:1], s[4:5], 0, v[0:1]
	v_lshlrev_b32_e32 v160, 10, v8
	v_lshl_add_u64 v[0:1], v[0:1], 0, v[160:161]
	s_lshl_b32 s20, s22, 1
	v_lshlrev_b32_e32 v2, 4, v6
	v_lshl_add_u64 v[0:1], v[0:1], 0, s[20:21]
	v_and_b32_e32 v4, 0x70, v2
	v_mov_b32_e32 v5, v161
	v_lshl_add_u64 v[0:1], v[0:1], 0, v[4:5]
	global_load_dwordx4 v[12:15], v[0:1], off
	s_movk_i32 s35, 0x140
	v_mul_lo_u32 v7, v7, s35
	v_add_u32_e32 v7, 0, v7
	v_lshlrev_b32_e32 v8, 7, v8
	v_add3_u32 v7, v7, v8, v4
	v_readlane_b32 s36, v250, 49
	v_readlane_b32 s37, v250, 50
	v_mov_b32_e32 v105, v161
	v_mov_b32_e32 v28, v7
	v_add_u32_e32 v0, 0x200, v6
	v_ashrrev_i32_e32 v7, 4, v0
	v_lshl_add_u32 v0, v7, 7, s23
	v_ashrrev_i32_e32 v1, 31, v0
	v_lshlrev_b64 v[0:1], 11, v[0:1]
	v_lshl_add_u64 v[0:1], s[4:5], 0, v[0:1]
	v_lshl_add_u64 v[0:1], v[0:1], 0, v[160:161]
	v_lshl_add_u64 v[0:1], v[0:1], 0, s[20:21]
	v_lshl_add_u64 v[0:1], v[0:1], 0, v[4:5]
	global_load_dwordx4 v[16:19], v[0:1], off
	v_mul_lo_u32 v7, v7, s35
	v_add_u32_e32 v7, 0, v7
	v_add3_u32 v7, v7, v8, v4
	v_mov_b32_e32 v29, v7
	v_add_u32_e32 v0, 0x400, v6
	v_ashrrev_i32_e32 v7, 4, v0
	v_lshl_add_u32 v0, v7, 7, s23
	v_ashrrev_i32_e32 v1, 31, v0
	v_lshlrev_b64 v[0:1], 11, v[0:1]
	v_lshl_add_u64 v[0:1], s[4:5], 0, v[0:1]
	v_lshl_add_u64 v[0:1], v[0:1], 0, v[160:161]
	v_lshl_add_u64 v[0:1], v[0:1], 0, s[20:21]
	v_lshl_add_u64 v[0:1], v[0:1], 0, v[4:5]
	global_load_dwordx4 v[20:23], v[0:1], off
	v_mul_lo_u32 v7, v7, s35
	v_add_u32_e32 v7, 0, v7
	v_add3_u32 v7, v7, v8, v4
	v_mov_b32_e32 v30, v7
	v_add_u32_e32 v0, 0x600, v6
	v_ashrrev_i32_e32 v7, 4, v0
	v_lshl_add_u32 v0, v7, 7, s23
	v_ashrrev_i32_e32 v1, 31, v0
	v_lshlrev_b64 v[0:1], 11, v[0:1]
	v_lshl_add_u64 v[0:1], s[4:5], 0, v[0:1]
	v_lshl_add_u64 v[0:1], v[0:1], 0, v[160:161]
	v_lshl_add_u64 v[0:1], v[0:1], 0, s[20:21]
	v_lshl_add_u64 v[0:1], v[0:1], 0, v[4:5]
	global_load_dwordx4 v[24:27], v[0:1], off
	v_mul_lo_u32 v5, v7, s35
	v_add_u32_e32 v5, 0, v5
	v_add3_u32 v4, v5, v8, v4
	v_mov_b32_e32 v31, v4
	v_ashrrev_i32_e32 v1, 3, v6
	v_and_b32_e32 v106, 0xffffffe0, v1
	v_lshlrev_b32_e32 v1, 2, v6
	v_and_b32_e32 v0, 16, v6
	v_and_b32_e32 v1, 12, v1
	v_or3_b32 v5, v0, v1, v106
	v_lshrrev_b32_e32 v2, 1, v6
	v_and_b32_e32 v0, 31, v6
	v_and_or_b32 v107, v2, s77, v0
	v_lshlrev_b32_e32 v160, 8, v107
	v_lshl_add_u64 v[0:1], s[36:37], 0, v[160:161]
	v_readlane_b32 s36, v252, 37
	v_and_b32_e32 v104, 16, v2
	v_readlane_b32 s37, v252, 38
	v_lshl_add_u64 v[0:1], v[0:1], 0, v[104:105]
	v_lshl_add_u64 v[2:3], s[36:37], 0, v[160:161]
	v_lshl_add_u64 v[2:3], v[2:3], 0, v[104:105]
	s_cmp_eq_u32 s70, 1
	s_cbranch_scc1 .Ld1skip_1
	global_load_dwordx4 v[126:129], v[0:1], off
	global_load_dwordx4 v[130:133], v[2:3], off
	global_load_dwordx4 v[134:137], v[0:1], off offset:32
	global_load_dwordx4 v[138:141], v[2:3], off offset:32
	global_load_dwordx4 v[142:145], v[0:1], off offset:64
	global_load_dwordx4 v[146:149], v[2:3], off offset:64
	global_load_dwordx4 v[150:153], v[0:1], off offset:96
	global_load_dwordx4 v[154:157], v[2:3], off offset:96
	global_load_dwordx4 v[174:177], v[0:1], off offset:128
	global_load_dwordx4 v[178:181], v[2:3], off offset:128
	global_load_dwordx4 v[182:185], v[0:1], off offset:160
	global_load_dwordx4 v[186:189], v[2:3], off offset:160
	global_load_dwordx4 v[190:193], v[0:1], off offset:192
	global_load_dwordx4 v[194:197], v[2:3], off offset:192
	global_load_dwordx4 v[198:201], v[0:1], off offset:224
	global_load_dwordx4 v[202:205], v[2:3], off offset:224
	s_mov_b32 s70, 1
	s_waitcnt vmcnt(19)
	ds_write_b128 v28, v[12:15]
	s_waitcnt vmcnt(18)
	ds_write_b128 v29, v[16:19]
	s_waitcnt vmcnt(17)
	ds_write_b128 v30, v[20:23]
	s_waitcnt vmcnt(16)
	ds_write_b128 v31, v[24:27]
	s_branch .Ld1join_1

; __device__ __forceinline__ f32x16 mfma32(bf16x8 a, bf16x8 b, f32x16 c) { return __builtin_amdgcn_mfma_f32_32x32x16_bf16(a, b, c, 0, 0, 0); }
; template <int STAGE>
; __device__ void dft_item(const bf16_t* __restrict__ src, bf16_t* __restrict__ dst, const bf16_t* __restrict__ Ct, const bf16_t* __restrict__ St,
;                          int N, int lgN, int rowbase, int j, int chblk, int S, int N1, int N2, LAS unsigned char* lds) {
;     ...
;   for (int ks = 0; ks < 8; ++ks) if (ks < nks) {
;     const unsigned rlo = (unsigned)(16 * ks + 8 * h + q4) * stride, rhi = rlo + 4u * stride;
;     const bf16x8 Ar = tr_frag(lds, rlo + colre, rhi + colre), Ai = tr_frag(lds, rlo + colim, rhi + colim);
;     a0 = mfma32(Ar, Bc[ks], a0); a0 = mfma32(Ai, Bs[ks], a0);
;     if (STAGE == 1) { a1 = mfma32(Ai, Bc[ks], a1); a2 = mfma32(Ar, Bs[ks], a2); }
;   }
;   const int chb = chblk * CB + chsub * 32;
;   if (STAGE == 1) {
;     const int mm = (j * kout) & (S - 1); const float fr = (float)mm / (float)S;
;     const float c = __builtin_amdgcn_cosf(fr), s = __builtin_amdgcn_sinf(fr);
;     const size_t orow = (size_t)(rowbase + kout * N2 + j) * 1024;
;     f32x16 re, im;
; #pragma unroll
;     for (int i = 0; i < 16; ++i) { const float yr = a0[i], yi = a1[i] - a2[i]; re[i] = yr * c + yi * s; im[i] = yi * c - yr * s; }
;     store_tile16(dst + orow + chb, re, 1.f, h); store_tile16(dst + orow + 512 + chb, im, 1.f, h);
.Ld1join_1:
	s_waitcnt lgkmcnt(0)
	s_barrier
	v_lshrrev_b32_e32 v4, 2, v6
	v_and_b32_e32 v1, 11, v4
	v_lshlrev_b32_e32 v0, 1, v5
	v_mul_u32_u24_e32 v1, 0x140, v1
	v_add3_u32 v124, 0, v0, v1
	ds_read_b64_tr_b16 v[36:37], v124
	ds_read_b64_tr_b16 v[38:39], v124 offset:1280
	ds_read_b64_tr_b16 v[20:21], v124 offset:128
	ds_read_b64_tr_b16 v[22:23], v124 offset:1408
	ds_read_b64_tr_b16 v[116:117], v124 offset:5120
	ds_read_b64_tr_b16 v[118:119], v124 offset:6400
	ds_read_b64_tr_b16 v[120:121], v124 offset:5248
	ds_read_b64_tr_b16 v[122:123], v124 offset:6528
	s_waitcnt vmcnt(15) lgkmcnt(6)
	v_mfma_f32_32x32x16_bf16 v[0:15], v[36:39], v[126:129], 0
	s_waitcnt vmcnt(14) lgkmcnt(4)
	v_mfma_f32_32x32x16_bf16 v[0:15], v[20:23], v[130:133], v[0:15]
	s_waitcnt vmcnt(13) lgkmcnt(2)
	v_mfma_f32_32x32x16_bf16 v[0:15], v[116:119], v[134:137], v[0:15]
	v_mfma_f32_32x32x16_bf16 v[16:31], v[20:23], v[126:129], 0
	v_mfma_f32_32x32x16_bf16 v[32:47], v[36:39], v[130:133], 0
	s_waitcnt vmcnt(12) lgkmcnt(0)
	v_mfma_f32_32x32x16_bf16 v[0:15], v[120:123], v[138:141], v[0:15]
	v_mfma_f32_32x32x16_bf16 v[16:31], v[120:123], v[134:137], v[16:31]
	v_mfma_f32_32x32x16_bf16 v[32:47], v[116:119], v[138:141], v[32:47]
	ds_read_b64_tr_b16 v[108:109], v124 offset:10240
	ds_read_b64_tr_b16 v[110:111], v124 offset:11520
	ds_read_b64_tr_b16 v[112:113], v124 offset:10368
	ds_read_b64_tr_b16 v[114:115], v124 offset:11648
	s_waitcnt vmcnt(11) lgkmcnt(2)
	v_mfma_f32_32x32x16_bf16 v[0:15], v[108:111], v[142:145], v[0:15]
	s_waitcnt vmcnt(10) lgkmcnt(0)
	v_mfma_f32_32x32x16_bf16 v[0:15], v[112:115], v[146:149], v[0:15]
	v_mfma_f32_32x32x16_bf16 v[16:31], v[112:115], v[142:145], v[16:31]
	v_mfma_f32_32x32x16_bf16 v[32:47], v[108:111], v[146:149], v[32:47]
	ds_read_b64_tr_b16 v[96:97], v124 offset:15360
	ds_read_b64_tr_b16 v[98:99], v124 offset:16640
	ds_read_b64_tr_b16 v[100:101], v124 offset:15488
	ds_read_b64_tr_b16 v[102:103], v124 offset:16768
	s_waitcnt vmcnt(9) lgkmcnt(2)
	v_mfma_f32_32x32x16_bf16 v[0:15], v[96:99], v[150:153], v[0:15]
	s_waitcnt vmcnt(8) lgkmcnt(0)
	v_mfma_f32_32x32x16_bf16 v[0:15], v[100:103], v[154:157], v[0:15]
	v_mfma_f32_32x32x16_bf16 v[16:31], v[100:103], v[150:153], v[16:31]
	v_mfma_f32_32x32x16_bf16 v[32:47], v[96:99], v[154:157], v[32:47]
	ds_read_b64_tr_b16 v[88:89], v124 offset:20480
	ds_read_b64_tr_b16 v[90:91], v124 offset:21760
	ds_read_b64_tr_b16 v[92:93], v124 offset:20608
	ds_read_b64_tr_b16 v[94:95], v124 offset:21888
	s_waitcnt vmcnt(7) lgkmcnt(2)
	v_mfma_f32_32x32x16_bf16 v[0:15], v[88:91], v[174:177], v[0:15]
	s_waitcnt vmcnt(6) lgkmcnt(0)
	v_mfma_f32_32x32x16_bf16 v[0:15], v[92:95], v[178:181], v[0:15]
	v_mfma_f32_32x32x16_bf16 v[16:31], v[92:95], v[174:177], v[16:31]
	v_mfma_f32_32x32x16_bf16 v[32:47], v[88:91], v[178:181], v[32:47]
	ds_read_b64_tr_b16 v[80:81], v124 offset:25600
	ds_read_b64_tr_b16 v[82:83], v124 offset:26880
	ds_read_b64_tr_b16 v[84:85], v124 offset:25728
	ds_read_b64_tr_b16 v[86:87], v124 offset:27008
	s_waitcnt vmcnt(5) lgkmcnt(2)
	v_mfma_f32_32x32x16_bf16 v[0:15], v[80:83], v[182:185], v[0:15]
	s_waitcnt vmcnt(4) lgkmcnt(0)
	v_mfma_f32_32x32x16_bf16 v[0:15], v[84:87], v[186:189], v[0:15]
	v_mfma_f32_32x32x16_bf16 v[16:31], v[84:87], v[182:185], v[16:31]
	v_mfma_f32_32x32x16_bf16 v[32:47], v[80:83], v[186:189], v[32:47]
	ds_read_b64_tr_b16 v[72:73], v124 offset:30720
	ds_read_b64_tr_b16 v[74:75], v124 offset:32000
	ds_read_b64_tr_b16 v[76:77], v124 offset:30848
	ds_read_b64_tr_b16 v[78:79], v124 offset:32128
	s_waitcnt vmcnt(3) lgkmcnt(2)
	v_mfma_f32_32x32x16_bf16 v[0:15], v[72:75], v[190:193], v[0:15]
	s_waitcnt vmcnt(2) lgkmcnt(0)
	v_mfma_f32_32x32x16_bf16 v[0:15], v[76:79], v[194:197], v[0:15]
	v_mfma_f32_32x32x16_bf16 v[16:31], v[76:79], v[190:193], v[16:31]
	v_mfma_f32_32x32x16_bf16 v[32:47], v[72:75], v[194:197], v[32:47]
	ds_read_b64_tr_b16 v[64:65], v124 offset:35840
	ds_read_b64_tr_b16 v[66:67], v124 offset:37120
	ds_read_b64_tr_b16 v[68:69], v124 offset:35968
	ds_read_b64_tr_b16 v[70:71], v124 offset:37248
	s_waitcnt vmcnt(1) lgkmcnt(2)
	v_mfma_f32_32x32x16_bf16 v[0:15], v[64:67], v[198:201], v[0:15]
	s_waitcnt vmcnt(0) lgkmcnt(0)
	v_mfma_f32_32x32x16_bf16 v[0:15], v[68:71], v[202:205], v[0:15]
	v_mfma_f32_32x32x16_bf16 v[32:47], v[64:67], v[202:205], v[32:47]
	v_mul_lo_u32 v56, v107, s34
	v_and_b32_e32 v56, 0x3fff, v56
	v_cvt_f32_u32_e32 v56, v56
	v_mul_f32_e32 v57, 0x38800000, v56
	v_mfma_f32_32x32x16_bf16 v[16:31], v[68:71], v[198:201], v[16:31]
	v_sin_f32_e32 v58, v57
	v_cos_f32_e32 v56, v57
	s_nop 9
	v_sub_f32_e32 v47, v31, v47
	v_sub_f32_e32 v46, v30, v46
	v_sub_f32_e32 v31, v23, v39
	v_sub_f32_e32 v30, v22, v38
	v_sub_f32_e32 v23, v21, v37
	v_sub_f32_e32 v22, v20, v36
	v_sub_f32_e32 v21, v19, v35
	v_sub_f32_e32 v20, v18, v34
	v_sub_f32_e32 v19, v17, v33
	v_sub_f32_e32 v18, v16, v32
	v_pk_mul_f32 v[16:17], v[58:59], v[0:1] op_sel_hi:[0,1]
	v_pk_fma_f32 v[16:17], v[56:57], v[18:19], v[16:17] op_sel_hi:[0,1,1] neg_lo:[0,0,1] neg_hi:[0,0,1]
	v_pk_mul_f32 v[18:19], v[58:59], v[18:19] op_sel_hi:[0,1]
	v_sub_f32_e32 v41, v25, v41
	v_sub_f32_e32 v40, v24, v40
	v_pk_fma_f32 v[24:25], v[56:57], v[0:1], v[18:19] op_sel_hi:[0,1,1]
	v_pk_mul_f32 v[0:1], v[58:59], v[2:3] op_sel_hi:[0,1]
	v_pk_fma_f32 v[18:19], v[56:57], v[20:21], v[0:1] op_sel_hi:[0,1,1] neg_lo:[0,0,1] neg_hi:[0,0,1]
	v_pk_mul_f32 v[0:1], v[58:59], v[20:21] op_sel_hi:[0,1]
	v_sub_f32_e32 v43, v27, v43
	v_sub_f32_e32 v42, v26, v42
	v_pk_fma_f32 v[26:27], v[56:57], v[2:3], v[0:1] op_sel_hi:[0,1,1]
	v_pk_mul_f32 v[0:1], v[58:59], v[4:5] op_sel_hi:[0,1]
	v_pk_fma_f32 v[20:21], v[56:57], v[22:23], v[0:1] op_sel_hi:[0,1,1] neg_lo:[0,0,1] neg_hi:[0,0,1]
; #define LAS __attribute__((address_space(3)))
; __device__ __forceinline__ int opaque_tid() { int t = threadIdx.x; asm volatile("" : "+v"(t)); return t; }
; __device__ __forceinline__ unsigned cvt_pk_bf16(float lo, float hi) { f32x2 v = {lo, hi}; bf16x2_t b = __builtin_convertvector(v, bf16x2_t); return __builtin_bit_cast(unsigned, b); }
; __device__ __forceinline__ float bf_lo(unsigned u) { return __uint_as_float(u << 16); }
; __device__ __forceinline__ float bf_hi(unsigned u) { return __uint_as_float(u & 0xffff0000u); }
; template <int STAGE>
; __device__ void dft_item(const bf16_t* __restrict__ src, bf16_t* __restrict__ dst, const bf16_t* __restrict__ Ct, const bf16_t* __restrict__ St,
;                          int N, int lgN, int rowbase, int j, int chblk, int S, int N1, int N2, LAS unsigned char* lds) {
;     ...
;     for (int i = 0; i < 16; ++i) { const float yr = a0[i], yi = a1[i] - a2[i]; re[i] = yr * c + yi * s; im[i] = yi * c - yr * s; }
;     store_tile16(dst + orow + chb, re, 1.f, h); store_tile16(dst + orow + 512 + chb, im, 1.f, h);
; __device__ void ret_state_item(const bf16_t* __restrict__ Kb, const bf16_t* __restrict__ Vb, bf16_t* __restrict__ STf, bf16_t* __restrict__ STb,
;                                int cidx, int head, float lgf2, float lgb2, LAS unsigned char* lds) {
;   const int tid = opaque_tid(), w = tid >> 6, l = tid & 63; const int row0 = cidx * 128;
;   constexpr unsigned VS = 576, KS = 320, OKF = 73728, OKB = 114688;
; #pragma unroll
;   for (int it = 0; it < 8; ++it) { const int q = tid + it * 512, j = q >> 5, c = q & 31;
;     *(LAS u32x4*)(lds + j * VS + c * 16) = *(const u32x4*)(Vb + (size_t)(row0 + j) * 1024 + head * 256 + c * 8); }
; #pragma unroll
;   for (int it = 0; it < 4; ++it) { const int q = tid + it * 512, j = q >> 4, c = q & 15;
;     const u32x4 v = *(const u32x4*)(Kb + (size_t)(row0 + j) * 512 + head * 128 + c * 8);
;     const float zf = __builtin_amdgcn_exp2f(lgf2 * (float)(127 - j)), zb = __builtin_amdgcn_exp2f(lgb2 * (float)j);
;     u32x4 of, ob;
; #pragma unroll
;     for (int i = 0; i < 4; ++i) { const float a = bf_lo(v[i]), b = bf_hi(v[i]); of[i] = cvt_pk_bf16(a * zf, b * zf); ob[i] = cvt_pk_bf16(a * zb, b * zb); }
;     *(LAS u32x4*)(lds + OKF + j * KS + c * 16) = of; *(LAS u32x4*)(lds + OKB + j * KS + c * 16) = ob; }
	v_pk_mul_f32 v[0:1], v[58:59], v[22:23] op_sel_hi:[0,1]
	v_sub_f32_e32 v45, v29, v45
	v_sub_f32_e32 v44, v28, v44
	v_pk_fma_f32 v[28:29], v[56:57], v[4:5], v[0:1] op_sel_hi:[0,1,1]
	v_pk_mul_f32 v[0:1], v[58:59], v[6:7] op_sel_hi:[0,1]
	v_pk_fma_f32 v[22:23], v[56:57], v[30:31], v[0:1] op_sel_hi:[0,1,1] neg_lo:[0,0,1] neg_hi:[0,0,1]
	v_pk_mul_f32 v[0:1], v[58:59], v[30:31] op_sel_hi:[0,1]
	v_pk_fma_f32 v[30:31], v[56:57], v[6:7], v[0:1] op_sel_hi:[0,1,1]
	v_pk_mul_f32 v[2:3], v[58:59], v[40:41] op_sel_hi:[0,1]
	v_pk_mul_f32 v[4:5], v[58:59], v[42:43] op_sel_hi:[0,1]
	v_pk_mul_f32 v[6:7], v[58:59], v[44:45] op_sel_hi:[0,1]
	v_pk_mul_f32 v[32:33], v[58:59], v[46:47] op_sel_hi:[0,1]
	v_pk_mul_f32 v[0:1], v[58:59], v[8:9] op_sel_hi:[0,1]
	v_pk_fma_f32 v[8:9], v[56:57], v[8:9], v[2:3] op_sel_hi:[0,1,1]
	v_pk_mul_f32 v[2:3], v[58:59], v[10:11] op_sel_hi:[0,1]
	v_pk_fma_f32 v[10:11], v[56:57], v[10:11], v[4:5] op_sel_hi:[0,1,1]
	v_pk_mul_f32 v[4:5], v[58:59], v[12:13] op_sel_hi:[0,1]
	v_pk_fma_f32 v[12:13], v[56:57], v[12:13], v[6:7] op_sel_hi:[0,1,1]
	v_pk_mul_f32 v[6:7], v[58:59], v[14:15] op_sel_hi:[0,1]
	v_pk_fma_f32 v[14:15], v[56:57], v[14:15], v[32:33] op_sel_hi:[0,1,1]
	v_lshl_add_u32 v32, v107, 7, s23
	v_ashrrev_i32_e32 v33, 31, v32
	v_add_u32_e32 v34, s22, v106
	v_lshlrev_b64 v[32:33], 11, v[32:33]
	v_lshl_add_u64 v[32:33], s[10:11], 0, v[32:33]
	v_ashrrev_i32_e32 v35, 31, v34
	v_lshl_add_u64 v[32:33], v[34:35], 1, v[32:33]
	v_cvt_pk_bf16_f32 v8, v8, v9
	v_cvt_pk_bf16_f32 v9, v10, v11
	v_cvt_pk_bf16_f32 v10, v12, v13
	v_cvt_pk_bf16_f32 v11, v14, v15
	v_pk_fma_f32 v[0:1], v[56:57], v[40:41], v[0:1] op_sel_hi:[0,1,1] neg_lo:[0,0,1] neg_hi:[0,0,1]
	v_pk_fma_f32 v[2:3], v[56:57], v[42:43], v[2:3] op_sel_hi:[0,1,1] neg_lo:[0,0,1] neg_hi:[0,0,1]
	v_pk_fma_f32 v[4:5], v[56:57], v[44:45], v[4:5] op_sel_hi:[0,1,1] neg_lo:[0,0,1] neg_hi:[0,0,1]
	v_pk_fma_f32 v[6:7], v[56:57], v[46:47], v[6:7] op_sel_hi:[0,1,1] neg_lo:[0,0,1] neg_hi:[0,0,1]
	v_lshl_add_u64 v[32:33], v[32:33], 0, v[104:105]
	v_permlane32_swap_b32_e32 v8, v10
	v_permlane32_swap_b32_e32 v9, v11
	v_cvt_pk_bf16_f32 v24, v24, v25
	v_cvt_pk_bf16_f32 v25, v26, v27
	v_cvt_pk_bf16_f32 v26, v28, v29
	v_cvt_pk_bf16_f32 v27, v30, v31
	global_store_dwordx4 v[32:33], v[8:11], off offset:32
	v_cvt_pk_bf16_f32 v0, v0, v1
	v_cvt_pk_bf16_f32 v1, v2, v3
	v_cvt_pk_bf16_f32 v8, v16, v17
	v_cvt_pk_bf16_f32 v9, v18, v19
	v_cvt_pk_bf16_f32 v10, v20, v21
	v_cvt_pk_bf16_f32 v11, v22, v23
	v_cvt_pk_bf16_f32 v2, v4, v5
	v_cvt_pk_bf16_f32 v3, v6, v7
	v_permlane32_swap_b32_e32 v24, v26
	v_permlane32_swap_b32_e32 v25, v27
	v_permlane32_swap_b32_e32 v8, v10
	v_permlane32_swap_b32_e32 v9, v11
	v_permlane32_swap_b32_e32 v0, v2
	v_permlane32_swap_b32_e32 v1, v3
	global_store_dwordx4 v[32:33], v[24:27], off
	global_store_dwordx4 v[32:33], v[8:11], off offset:1024
	global_store_dwordx4 v[32:33], v[0:3], off offset:1056
	s_barrier
	s_branch .LBB0_432
.LBB0_437:
	v_mov_b32_e32 v152, v214
	s_and_b32 s12, s6, 0xffffff80
	s_lshl_b32 s20, s13, 8
	s_lshl_b32 s13, s13, 9
	v_ashrrev_i32_e32 v13, 5, v152
	v_and_b32_e32 v153, 31, v152
	s_add_u32 s34, s14, s13
	v_add_u32_e32 v2, s12, v13
	s_addc_u32 s35, s15, 0
	v_lshlrev_b32_e32 v160, 4, v153
	v_ashrrev_i32_e32 v3, 31, v2
	v_lshl_add_u64 v[0:1], s[34:35], 0, v[160:161]
	v_lshlrev_b64 v[2:3], 11, v[2:3]
	v_add_u32_e32 v47, 0x200, v152
	v_lshl_add_u64 v[2:3], v[0:1], 0, v[2:3]
	v_ashrrev_i32_e32 v50, 5, v47
	global_load_dwordx4 v[14:17], v[2:3], off
	v_add_u32_e32 v2, s12, v50
	v_ashrrev_i32_e32 v3, 31, v2
	v_lshlrev_b64 v[2:3], 11, v[2:3]
	v_add_u32_e32 v52, 0x400, v152
	v_lshl_add_u64 v[2:3], v[0:1], 0, v[2:3]
	v_ashrrev_i32_e32 v53, 5, v52
	global_load_dwordx4 v[18:21], v[2:3], off
	v_add_u32_e32 v2, s12, v53
	v_ashrrev_i32_e32 v3, 31, v2
	v_lshlrev_b64 v[2:3], 11, v[2:3]
	v_add_u32_e32 v12, 0x600, v152
	v_lshl_add_u64 v[2:3], v[0:1], 0, v[2:3]
	v_ashrrev_i32_e32 v54, 5, v12
	global_load_dwordx4 v[22:25], v[2:3], off
	v_add_u32_e32 v2, s12, v54
	v_ashrrev_i32_e32 v3, 31, v2
	v_lshlrev_b64 v[2:3], 11, v[2:3]
	v_lshl_add_u64 v[2:3], v[0:1], 0, v[2:3]
	global_load_dwordx4 v[26:29], v[2:3], off
	v_add_u32_e32 v2, 0x800, v152
	v_ashrrev_i32_e32 v55, 5, v2
	v_add_u32_e32 v2, s12, v55
	v_ashrrev_i32_e32 v3, 31, v2
	v_lshlrev_b64 v[2:3], 11, v[2:3]
	v_lshl_add_u64 v[2:3], v[0:1], 0, v[2:3]
	global_load_dwordx4 v[30:33], v[2:3], off
	v_add_u32_e32 v2, 0xa00, v152
	v_ashrrev_i32_e32 v56, 5, v2
	v_add_u32_e32 v2, s12, v56
	v_ashrrev_i32_e32 v3, 31, v2
	v_lshlrev_b64 v[2:3], 11, v[2:3]
	v_lshl_add_u64 v[2:3], v[0:1], 0, v[2:3]
	global_load_dwordx4 v[34:37], v[2:3], off
	v_add_u32_e32 v2, 0xc00, v152
	v_ashrrev_i32_e32 v57, 5, v2
	v_add_u32_e32 v2, s12, v57
	v_ashrrev_i32_e32 v3, 31, v2
	v_lshlrev_b64 v[2:3], 11, v[2:3]
	v_lshl_add_u64 v[2:3], v[0:1], 0, v[2:3]
	global_load_dwordx4 v[38:41], v[2:3], off
	v_add_u32_e32 v2, 0xe00, v152
	v_ashrrev_i32_e32 v58, 5, v2
	v_add_u32_e32 v2, s12, v58
	v_ashrrev_i32_e32 v3, 31, v2
	v_lshlrev_b64 v[2:3], 11, v[2:3]
	v_lshl_add_u64 v[0:1], v[0:1], 0, v[2:3]
	global_load_dwordx4 v[42:45], v[0:1], off
	v_lshlrev_b32_e32 v0, 4, v152
	v_ashrrev_i32_e32 v59, 4, v152
	v_add_u32_e32 v46, 0, v160
	s_add_u32 s34, s52, s20
	v_and_b32_e32 v160, 0xf0, v0
	v_add_u32_e32 v0, s12, v59
	s_addc_u32 s35, s62, 0
	v_ashrrev_i32_e32 v1, 31, v0
	v_lshl_add_u64 v[8:9], s[34:35], 0, v[160:161]
	v_lshlrev_b64 v[0:1], 10, v[0:1]
	v_lshl_add_u64 v[0:1], v[8:9], 0, v[0:1]
	global_load_dwordx4 v[4:7], v[0:1], off
	v_ashrrev_i32_e32 v47, 4, v47
	v_add_u32_e32 v0, s12, v47
	v_ashrrev_i32_e32 v1, 31, v0
	v_lshlrev_b64 v[0:1], 10, v[0:1]
	v_lshl_add_u64 v[0:1], v[8:9], 0, v[0:1]
	global_load_dwordx4 v[0:3], v[0:1], off
	v_ashrrev_i32_e32 v190, 4, v52
	v_add_u32_e32 v190, s12, v190
	v_ashrrev_i32_e32 v191, 31, v190
	v_lshlrev_b64 v[190:191], 10, v[190:191]
	v_lshl_add_u64 v[190:191], v[8:9], 0, v[190:191]
	global_load_dwordx4 v[182:185], v[190:191], off
	v_ashrrev_i32_e32 v190, 4, v12
	v_add_u32_e32 v190, s12, v190
	v_ashrrev_i32_e32 v191, 31, v190
	v_lshlrev_b64 v[190:191], 10, v[190:191]
	v_lshl_add_u64 v[190:191], v[8:9], 0, v[190:191]
	global_load_dwordx4 v[186:189], v[190:191], off
	v_mad_u64_u32 v[48:49], s[34:35], v13, s54, v[46:47]
	v_mad_u64_u32 v[50:51], s[34:35], v50, s54, v[46:47]
	v_sub_u32_e32 v13, 0x7f, v59
	v_cvt_f32_i32_e32 v13, v13
	s_waitcnt vmcnt(11)
; #define LAS __attribute__((address_space(3)))
; __device__ __forceinline__ unsigned cvt_pk_bf16(float lo, float hi) { f32x2 v = {lo, hi}; bf16x2_t b = __builtin_convertvector(v, bf16x2_t); return __builtin_bit_cast(unsigned, b); }
; __device__ __forceinline__ float bf_lo(unsigned u) { return __uint_as_float(u << 16); }
; __device__ __forceinline__ float bf_hi(unsigned u) { return __uint_as_float(u & 0xffff0000u); }
; __device__ void ret_state_item(const bf16_t* __restrict__ Kb, const bf16_t* __restrict__ Vb, bf16_t* __restrict__ STf, bf16_t* __restrict__ STb,
;                                int cidx, int head, float lgf2, float lgb2, LAS unsigned char* lds) {
;     ...
;   for (int it = 0; it < 8; ++it) { const int q = tid + it * 512, j = q >> 5, c = q & 31;
;     *(LAS u32x4*)(lds + j * VS + c * 16) = *(const u32x4*)(Vb + (size_t)(row0 + j) * 1024 + head * 256 + c * 8); }
; #pragma unroll
;   for (int it = 0; it < 4; ++it) { const int q = tid + it * 512, j = q >> 4, c = q & 15;
;     const u32x4 v = *(const u32x4*)(Kb + (size_t)(row0 + j) * 512 + head * 128 + c * 8);
;     const float zf = __builtin_amdgcn_exp2f(lgf2 * (float)(127 - j)), zb = __builtin_amdgcn_exp2f(lgb2 * (float)j);
;     u32x4 of, ob;
; #pragma unroll
;     for (int i = 0; i < 4; ++i) { const float a = bf_lo(v[i]), b = bf_hi(v[i]); of[i] = cvt_pk_bf16(a * zf, b * zf); ob[i] = cvt_pk_bf16(a * zb, b * zb); }
;     *(LAS u32x4*)(lds + OKF + j * KS + c * 16) = of; *(LAS u32x4*)(lds + OKB + j * KS + c * 16) = ob; }
;   __syncthreads();
;   const int i16 = l & 15, q4 = i16 >> 2, p4 = i16 & 3, G1 = (l >> 4) & 1, h = l >> 5;
	ds_write_b128 v48, v[14:17]
	s_waitcnt vmcnt(10)
	ds_write_b128 v50, v[18:21]
	v_mad_u64_u32 v[14:15], s[34:35], v53, s54, v[46:47]
	v_mul_f32_e32 v13, v10, v13
	s_add_i32 s13, 0, 0x12000
	s_add_i32 s7, s7, s90
	s_waitcnt vmcnt(9)
	ds_write_b128 v14, v[22:25]
	v_mad_u64_u32 v[14:15], s[34:35], v54, s54, v[46:47]
	v_exp_f32_e32 v22, v13
	v_add_u32_e32 v25, s13, v160
	s_waitcnt vmcnt(8)
	ds_write_b128 v14, v[26:29]
	v_mad_u64_u32 v[14:15], s[34:35], v55, s54, v[46:47]
	v_ashrrev_i32_e32 v29, 4, v52
	s_add_i32 s13, 0, 0x1c000
	v_add_u32_e32 v28, s13, v160
	s_movk_i32 s13, 0x140
	s_waitcnt vmcnt(7)
	ds_write_b128 v14, v[30:33]
	v_mad_u64_u32 v[14:15], s[34:35], v56, s54, v[46:47]
	s_waitcnt vmcnt(6)
	ds_write_b128 v14, v[34:37]
	v_mad_u64_u32 v[14:15], s[34:35], v57, s54, v[46:47]
	s_waitcnt vmcnt(5)
	ds_write_b128 v14, v[38:41]
	v_mad_u64_u32 v[14:15], s[34:35], v58, s54, v[46:47]
	s_waitcnt vmcnt(4)
	ds_write_b128 v14, v[42:45]
	v_cvt_f32_i32_e32 v14, v59
	v_mul_f32_e32 v13, v11, v14
	v_exp_f32_e32 v24, v13
	s_waitcnt vmcnt(3)
	v_lshlrev_b32_e32 v18, 16, v4
	v_and_b32_e32 v19, 0xffff0000, v4
	v_pk_mul_f32 v[20:21], v[22:23], v[18:19] op_sel_hi:[0,1]
	v_cvt_pk_bf16_f32 v4, v20, v21
	v_lshlrev_b32_e32 v20, 16, v5
	v_and_b32_e32 v21, 0xffff0000, v5
	v_pk_mul_f32 v[18:19], v[24:25], v[18:19] op_sel_hi:[0,1]
	v_pk_mul_f32 v[26:27], v[22:23], v[20:21] op_sel_hi:[0,1]
	v_pk_mul_f32 v[20:21], v[24:25], v[20:21] op_sel_hi:[0,1]
	v_cvt_pk_bf16_f32 v18, v18, v19
	v_cvt_pk_bf16_f32 v19, v20, v21
	v_lshlrev_b32_e32 v20, 16, v6
	v_and_b32_e32 v21, 0xffff0000, v6
	v_cvt_pk_bf16_f32 v5, v26, v27
	v_pk_mul_f32 v[26:27], v[22:23], v[20:21] op_sel_hi:[0,1]
	v_cvt_pk_bf16_f32 v6, v26, v27
	v_lshlrev_b32_e32 v26, 16, v7
	v_and_b32_e32 v27, 0xffff0000, v7
	v_pk_mul_f32 v[22:23], v[22:23], v[26:27] op_sel_hi:[0,1]
	v_pk_mul_f32 v[20:21], v[24:25], v[20:21] op_sel_hi:[0,1]
	v_cvt_pk_bf16_f32 v7, v22, v23
	v_pk_mul_f32 v[22:23], v[24:25], v[26:27] op_sel_hi:[0,1]
	v_mul_lo_u32 v13, v59, s13
	v_cvt_pk_bf16_f32 v20, v20, v21
	v_cvt_pk_bf16_f32 v21, v22, v23
	v_add_u32_e32 v22, v25, v13
	ds_write_b128 v22, v[4:7]
	v_sub_u32_e32 v4, 0x7f, v47
	v_ashrrev_i32_e32 v24, 4, v12
	v_cvt_f32_i32_e32 v22, v4
	v_cvt_f32_i32_e32 v9, v47
	v_add_u32_e32 v8, v28, v13
	ds_write_b128 v8, v[18:21]
	v_mul_f32_e32 v8, v10, v22
	v_exp_f32_e32 v8, v8
	v_mul_f32_e32 v9, v11, v9
	v_exp_f32_e32 v12, v9
	s_waitcnt vmcnt(2)
	v_lshlrev_b32_e32 v18, 16, v0
	v_and_b32_e32 v19, 0xffff0000, v0
	v_pk_mul_f32 v[20:21], v[8:9], v[18:19] op_sel_hi:[0,1]
	v_cvt_pk_bf16_f32 v0, v20, v21
	v_lshlrev_b32_e32 v20, 16, v1
	v_and_b32_e32 v21, 0xffff0000, v1
	v_pk_mul_f32 v[18:19], v[12:13], v[18:19] op_sel_hi:[0,1]
	v_pk_mul_f32 v[22:23], v[8:9], v[20:21] op_sel_hi:[0,1]
	v_pk_mul_f32 v[20:21], v[12:13], v[20:21] op_sel_hi:[0,1]
	v_cvt_pk_bf16_f32 v18, v18, v19
	v_cvt_pk_bf16_f32 v19, v20, v21
	v_lshlrev_b32_e32 v20, 16, v2
	v_and_b32_e32 v21, 0xffff0000, v2
	v_cvt_pk_bf16_f32 v1, v22, v23
	v_pk_mul_f32 v[22:23], v[8:9], v[20:21] op_sel_hi:[0,1]
	v_cvt_pk_bf16_f32 v2, v22, v23
	v_lshlrev_b32_e32 v22, 16, v3
	v_and_b32_e32 v23, 0xffff0000, v3
	v_pk_mul_f32 v[8:9], v[8:9], v[22:23] op_sel_hi:[0,1]
	v_pk_mul_f32 v[20:21], v[12:13], v[20:21] op_sel_hi:[0,1]
	v_cvt_pk_bf16_f32 v3, v8, v9
	v_pk_mul_f32 v[8:9], v[12:13], v[22:23] op_sel_hi:[0,1]
	v_cvt_pk_bf16_f32 v20, v20, v21
	v_cvt_pk_bf16_f32 v21, v8, v9
	v_mul_lo_u32 v8, v47, s13
	v_add_u32_e32 v9, v25, v8
	ds_write_b128 v9, v[0:3]
	v_sub_u32_e32 v0, 0x7f, v29
	v_cvt_f32_i32_e32 v0, v0
	v_cvt_f32_i32_e32 v2, v29
	v_add_u32_e32 v1, v28, v8
	ds_write_b128 v1, v[18:21]
	v_mul_f32_e32 v0, v10, v0
	v_exp_f32_e32 v8, v0
	v_mul_f32_e32 v0, v11, v2
	v_exp_f32_e32 v18, v0
	s_waitcnt vmcnt(1)
	v_mov_b64_e32 v[14:15], v[182:183]
	v_mov_b64_e32 v[16:17], v[184:185]
	v_lshlrev_b32_e32 v2, 16, v14
	v_and_b32_e32 v3, 0xffff0000, v14
	v_pk_mul_f32 v[0:1], v[8:9], v[2:3] op_sel_hi:[0,1]
	v_pk_mul_f32 v[2:3], v[18:19], v[2:3] op_sel_hi:[0,1]
	v_cvt_pk_bf16_f32 v12, v2, v3
	v_lshlrev_b32_e32 v2, 16, v15
	v_and_b32_e32 v3, 0xffff0000, v15
	v_pk_mul_f32 v[14:15], v[8:9], v[2:3] op_sel_hi:[0,1]
	v_cvt_pk_bf16_f32 v0, v0, v1
	v_cvt_pk_bf16_f32 v1, v14, v15
	v_pk_mul_f32 v[2:3], v[18:19], v[2:3] op_sel_hi:[0,1]
	v_lshlrev_b32_e32 v14, 16, v16
	v_and_b32_e32 v15, 0xffff0000, v16
	v_lshlrev_b32_e32 v16, 16, v17
	v_and_b32_e32 v17, 0xffff0000, v17
	v_cvt_pk_bf16_f32 v13, v2, v3
	v_pk_mul_f32 v[2:3], v[8:9], v[14:15] op_sel_hi:[0,1]
	v_pk_mul_f32 v[8:9], v[8:9], v[16:17] op_sel_hi:[0,1]
	v_cvt_pk_bf16_f32 v2, v2, v3
	v_pk_mul_f32 v[14:15], v[18:19], v[14:15] op_sel_hi:[0,1]
	v_cvt_pk_bf16_f32 v3, v8, v9
	v_pk_mul_f32 v[8:9], v[18:19], v[16:17] op_sel_hi:[0,1]
	v_cvt_pk_bf16_f32 v14, v14, v15
	v_cvt_pk_bf16_f32 v15, v8, v9
	v_mul_lo_u32 v8, v29, s13
	v_add_u32_e32 v9, v25, v8
	ds_write_b128 v9, v[0:3]
	v_sub_u32_e32 v0, 0x7f, v24
	v_cvt_f32_i32_e32 v0, v0
	v_cvt_f32_i32_e32 v2, v24
	v_add_u32_e32 v1, v28, v8
	ds_write_b128 v1, v[12:15]
	v_mul_f32_e32 v0, v10, v0
	v_exp_f32_e32 v8, v0
	v_mul_f32_e32 v0, v11, v2
	v_exp_f32_e32 v10, v0
	s_waitcnt vmcnt(0)
	v_mov_b64_e32 v[4:5], v[186:187]
	v_mov_b64_e32 v[6:7], v[188:189]
	v_lshlrev_b32_e32 v2, 16, v4
	v_and_b32_e32 v3, 0xffff0000, v4
	v_pk_mul_f32 v[0:1], v[8:9], v[2:3] op_sel_hi:[0,1]
	v_pk_mul_f32 v[2:3], v[10:11], v[2:3] op_sel_hi:[0,1]
	v_cvt_pk_bf16_f32 v4, v2, v3
	v_lshlrev_b32_e32 v2, 16, v5
	v_and_b32_e32 v3, 0xffff0000, v5
	v_pk_mul_f32 v[12:13], v[8:9], v[2:3] op_sel_hi:[0,1]
	v_cvt_pk_bf16_f32 v0, v0, v1
	v_cvt_pk_bf16_f32 v1, v12, v13
	v_pk_mul_f32 v[2:3], v[10:11], v[2:3] op_sel_hi:[0,1]
	v_lshlrev_b32_e32 v12, 16, v6
	v_and_b32_e32 v13, 0xffff0000, v6
	v_cvt_pk_bf16_f32 v5, v2, v3
	v_pk_mul_f32 v[2:3], v[8:9], v[12:13] op_sel_hi:[0,1]
	v_pk_mul_f32 v[12:13], v[10:11], v[12:13] op_sel_hi:[0,1]
	v_cvt_pk_bf16_f32 v6, v12, v13
	v_lshlrev_b32_e32 v12, 16, v7
	v_and_b32_e32 v13, 0xffff0000, v7
	v_pk_mul_f32 v[8:9], v[8:9], v[12:13] op_sel_hi:[0,1]
	v_cvt_pk_bf16_f32 v2, v2, v3
	v_cvt_pk_bf16_f32 v3, v8, v9
	v_pk_mul_f32 v[8:9], v[10:11], v[12:13] op_sel_hi:[0,1]
	v_cvt_pk_bf16_f32 v7, v8, v9
	v_mul_lo_u32 v8, v24, s13
	v_add_u32_e32 v9, v25, v8
	ds_write_b128 v9, v[0:3]
	v_add_u32_e32 v0, v28, v8
	ds_write_b128 v0, v[4:7]
	v_lshrrev_b32_e32 v0, 2, v152
	v_and_b32_e32 v1, 16, v152
	v_lshlrev_b32_e32 v2, 2, v152
	v_and_or_b32 v1, v2, 12, v1
	v_and_b32_e32 v5, 11, v0
	v_and_b32_e32 v0, 0xffffffc0, v152
	v_lshlrev_b32_e32 v4, 1, v1
	v_add_u32_e32 v6, 0, v0
	v_mul_u32_u24_e32 v0, 0x140, v5
	v_add3_u32 v154, 0, v0, v4
	v_mul_u32_u24_e32 v5, 0x240, v5
	v_add_u32_e32 v12, 0x12000, v154
	v_add3_u32 v132, v6, v4, v5
	v_add_u32_e32 v14, 0x1c000, v154
	v_add_u32_e32 v15, 0x1c500, v154
	s_waitcnt lgkmcnt(0)
	s_barrier
; __device__ __forceinline__ f32x16 mfma32(bf16x8 a, bf16x8 b, f32x16 c) { return __builtin_amdgcn_mfma_f32_32x32x16_bf16(a, b, c, 0, 0, 0); }
; __device__ void ret_state_item(const bf16_t* __restrict__ Kb, const bf16_t* __restrict__ Vb, bf16_t* __restrict__ STf, bf16_t* __restrict__ STb,
;                                int cidx, int head, float lgf2, float lgb2, LAS unsigned char* lds) {
;     ...
;   const int i16 = l & 15, q4 = i16 >> 2, p4 = i16 & 3, G1 = (l >> 4) & 1, h = l >> 5;
;   const unsigned cofs = (unsigned)(16 * G1 + 4 * p4) * 2u;
;   f32x16 af[4], ab[4];
; #pragma unroll
;   for (int i = 0; i < 4; ++i) { af[i] = (f32x16){}; ab[i] = (f32x16){}; }
;   for (int ks = 0; ks < 8; ++ks) {
;     const unsigned r = (unsigned)(16 * ks + 8 * h + q4);
;     const bf16x8 Bv = tr_frag(lds, r * VS + w * 64 + cofs, (r + 4) * VS + w * 64 + cofs);
; #pragma unroll
;     for (int dt = 0; dt < 4; ++dt) {
;       const bf16x8 Af = tr_frag(lds, OKF + r * KS + dt * 64 + cofs, OKF + (r + 4) * KS + dt * 64 + cofs);
;       const bf16x8 Ab = tr_frag(lds, OKB + r * KS + dt * 64 + cofs, OKB + (r + 4) * KS + dt * 64 + cofs);
;       af[dt] = mfma32(Af, Bv, af[dt]); ab[dt] = mfma32(Ab, Bv, ab[dt]);
;     }
;   }
	v_add_u32_e32 v13, 0x12500, v154
	ds_read_b64_tr_b16 v[0:1], v12
	ds_read_b64_tr_b16 v[2:3], v13
	ds_read_b64_tr_b16 v[4:5], v132
	ds_read_b64_tr_b16 v[6:7], v132 offset:2304
	ds_read_b64_tr_b16 v[8:9], v14
	ds_read_b64_tr_b16 v[10:11], v15
	s_waitcnt lgkmcnt(2)
	v_mfma_f32_32x32x16_bf16 v[112:127], v[0:3], v[4:7], 0
	v_add_u32_e32 v133, 0x13400, v154
	v_add_u32_e32 v135, 0x1d400, v154
	v_add_u32_e32 v155, 0x1d900, v154
	v_add_u32_e32 v134, 0x13900, v154
	v_readlane_b32 s12, v250, 51
	v_readlane_b32 s13, v250, 52
	s_waitcnt lgkmcnt(0)
	v_mfma_f32_32x32x16_bf16 v[96:111], v[8:11], v[4:7], 0
	ds_read_b64_tr_b16 v[0:1], v12 offset:64
	ds_read_b64_tr_b16 v[2:3], v13 offset:64
	ds_read_b64_tr_b16 v[8:9], v14 offset:64
	ds_read_b64_tr_b16 v[10:11], v15 offset:64
	s_waitcnt lgkmcnt(2)
	v_mfma_f32_32x32x16_bf16 v[80:95], v[0:3], v[4:7], 0
	s_waitcnt lgkmcnt(0)
	v_mfma_f32_32x32x16_bf16 v[64:79], v[8:11], v[4:7], 0
	ds_read_b64_tr_b16 v[0:1], v12 offset:128
	ds_read_b64_tr_b16 v[2:3], v13 offset:128
	ds_read_b64_tr_b16 v[8:9], v14 offset:128
	ds_read_b64_tr_b16 v[10:11], v15 offset:128
	s_waitcnt lgkmcnt(2)
	v_mfma_f32_32x32x16_bf16 v[48:63], v[0:3], v[4:7], 0
	s_waitcnt lgkmcnt(0)
	v_mfma_f32_32x32x16_bf16 v[16:31], v[8:11], v[4:7], 0
	ds_read_b64_tr_b16 v[0:1], v12 offset:192
	ds_read_b64_tr_b16 v[2:3], v13 offset:192
	ds_read_b64_tr_b16 v[8:9], v14 offset:192
	ds_read_b64_tr_b16 v[10:11], v15 offset:192
	ds_read_b64_tr_b16 v[128:129], v133
	ds_read_b64_tr_b16 v[130:131], v134
	ds_read_b64_tr_b16 v[156:157], v132 offset:9216
	ds_read_b64_tr_b16 v[158:159], v132 offset:11520
	ds_read_b64_tr_b16 v[174:175], v135
	ds_read_b64_tr_b16 v[176:177], v155
	s_waitcnt lgkmcnt(2)
	v_mfma_f32_32x32x16_bf16 v[112:127], v[128:131], v[156:159], v[112:127]
	s_waitcnt lgkmcnt(0)
	v_mfma_f32_32x32x16_bf16 v[96:111], v[174:177], v[156:159], v[96:111]
	ds_read_b64_tr_b16 v[128:129], v133 offset:64
	ds_read_b64_tr_b16 v[130:131], v134 offset:64
	ds_read_b64_tr_b16 v[174:175], v135 offset:64
	ds_read_b64_tr_b16 v[176:177], v155 offset:64
	s_waitcnt lgkmcnt(2)
	v_mfma_f32_32x32x16_bf16 v[80:95], v[128:131], v[156:159], v[80:95]
	s_waitcnt lgkmcnt(0)
	v_mfma_f32_32x32x16_bf16 v[64:79], v[174:177], v[156:159], v[64:79]
	ds_read_b64_tr_b16 v[128:129], v133 offset:128
	ds_read_b64_tr_b16 v[130:131], v134 offset:128
	ds_read_b64_tr_b16 v[174:175], v135 offset:128
	ds_read_b64_tr_b16 v[176:177], v155 offset:128
	s_waitcnt lgkmcnt(2)
	v_mfma_f32_32x32x16_bf16 v[48:63], v[128:131], v[156:159], v[48:63]
	s_waitcnt lgkmcnt(0)
	v_mfma_f32_32x32x16_bf16 v[16:31], v[174:177], v[156:159], v[16:31]
	ds_read_b64_tr_b16 v[128:129], v133 offset:192
	ds_read_b64_tr_b16 v[130:131], v134 offset:192
	ds_read_b64_tr_b16 v[174:175], v135 offset:192
	ds_read_b64_tr_b16 v[176:177], v155 offset:192
	v_add_u32_e32 v133, 0x14800, v154
	v_add_u32_e32 v135, 0x1e800, v154
	v_add_u32_e32 v155, 0x1ed00, v154
	v_add_u32_e32 v134, 0x14d00, v154
	v_mfma_f32_32x32x16_bf16 v[32:47], v[0:3], v[4:7], 0
	v_mfma_f32_32x32x16_bf16 v[0:15], v[8:11], v[4:7], 0
	s_waitcnt lgkmcnt(2)
	v_mfma_f32_32x32x16_bf16 v[32:47], v[128:131], v[156:159], v[32:47]
	s_waitcnt lgkmcnt(0)
	v_mfma_f32_32x32x16_bf16 v[0:15], v[174:177], v[156:159], v[0:15]
	ds_read_b64_tr_b16 v[128:129], v133
	ds_read_b64_tr_b16 v[130:131], v134
	ds_read_b64_tr_b16 v[156:157], v132 offset:18432
	ds_read_b64_tr_b16 v[158:159], v132 offset:20736
	ds_read_b64_tr_b16 v[174:175], v135
	ds_read_b64_tr_b16 v[176:177], v155
	s_waitcnt lgkmcnt(2)
	v_mfma_f32_32x32x16_bf16 v[112:127], v[128:131], v[156:159], v[112:127]
	s_waitcnt lgkmcnt(0)
	v_mfma_f32_32x32x16_bf16 v[96:111], v[174:177], v[156:159], v[96:111]
	ds_read_b64_tr_b16 v[128:129], v133 offset:64
	ds_read_b64_tr_b16 v[130:131], v134 offset:64
	ds_read_b64_tr_b16 v[174:175], v135 offset:64
	ds_read_b64_tr_b16 v[176:177], v155 offset:64
	s_waitcnt lgkmcnt(2)
	v_mfma_f32_32x32x16_bf16 v[80:95], v[128:131], v[156:159], v[80:95]
	s_waitcnt lgkmcnt(0)
	v_mfma_f32_32x32x16_bf16 v[64:79], v[174:177], v[156:159], v[64:79]
	ds_read_b64_tr_b16 v[128:129], v133 offset:128
	ds_read_b64_tr_b16 v[130:131], v134 offset:128
	ds_read_b64_tr_b16 v[174:175], v135 offset:128
	ds_read_b64_tr_b16 v[176:177], v155 offset:128
	s_waitcnt lgkmcnt(2)
	v_mfma_f32_32x32x16_bf16 v[48:63], v[128:131], v[156:159], v[48:63]
	s_waitcnt lgkmcnt(0)
	v_mfma_f32_32x32x16_bf16 v[16:31], v[174:177], v[156:159], v[16:31]
	ds_read_b64_tr_b16 v[128:129], v133 offset:192
	ds_read_b64_tr_b16 v[130:131], v134 offset:192
	ds_read_b64_tr_b16 v[174:175], v135 offset:192
	ds_read_b64_tr_b16 v[176:177], v155 offset:192
	v_add_u32_e32 v133, 0x15c00, v154
	v_add_u32_e32 v135, 0x1fc00, v154
	v_add_u32_e32 v155, 0x20100, v154
	v_add_u32_e32 v134, 0x16100, v154
	s_waitcnt lgkmcnt(2)
	v_mfma_f32_32x32x16_bf16 v[32:47], v[128:131], v[156:159], v[32:47]
	s_waitcnt lgkmcnt(0)
	v_mfma_f32_32x32x16_bf16 v[0:15], v[174:177], v[156:159], v[0:15]
	ds_read_b64_tr_b16 v[128:129], v133
	ds_read_b64_tr_b16 v[130:131], v134
	ds_read_b64_tr_b16 v[156:157], v132 offset:27648
	ds_read_b64_tr_b16 v[158:159], v132 offset:29952
	ds_read_b64_tr_b16 v[174:175], v135
	ds_read_b64_tr_b16 v[176:177], v155
	s_waitcnt lgkmcnt(2)
	v_mfma_f32_32x32x16_bf16 v[112:127], v[128:131], v[156:159], v[112:127]
	s_waitcnt lgkmcnt(0)
	v_mfma_f32_32x32x16_bf16 v[96:111], v[174:177], v[156:159], v[96:111]
	ds_read_b64_tr_b16 v[128:129], v133 offset:64
	ds_read_b64_tr_b16 v[130:131], v134 offset:64
	ds_read_b64_tr_b16 v[174:175], v135 offset:64
	ds_read_b64_tr_b16 v[176:177], v155 offset:64
	s_waitcnt lgkmcnt(2)
	v_mfma_f32_32x32x16_bf16 v[80:95], v[128:131], v[156:159], v[80:95]
	s_waitcnt lgkmcnt(0)
; __device__ __forceinline__ f32x16 mfma32(bf16x8 a, bf16x8 b, f32x16 c) { return __builtin_amdgcn_mfma_f32_32x32x16_bf16(a, b, c, 0, 0, 0); }
; __device__ void ret_state_item(const bf16_t* __restrict__ Kb, const bf16_t* __restrict__ Vb, bf16_t* __restrict__ STf, bf16_t* __restrict__ STb,
;                                int cidx, int head, float lgf2, float lgb2, LAS unsigned char* lds) {
;     ...
;   for (int ks = 0; ks < 8; ++ks) {
;     const unsigned r = (unsigned)(16 * ks + 8 * h + q4);
;     const bf16x8 Bv = tr_frag(lds, r * VS + w * 64 + cofs, (r + 4) * VS + w * 64 + cofs);
; #pragma unroll
;     for (int dt = 0; dt < 4; ++dt) {
;       const bf16x8 Af = tr_frag(lds, OKF + r * KS + dt * 64 + cofs, OKF + (r + 4) * KS + dt * 64 + cofs);
;       const bf16x8 Ab = tr_frag(lds, OKB + r * KS + dt * 64 + cofs, OKB + (r + 4) * KS + dt * 64 + cofs);
;       af[dt] = mfma32(Af, Bv, af[dt]); ab[dt] = mfma32(Ab, Bv, ab[dt]);
;     }
;   }
	v_mfma_f32_32x32x16_bf16 v[64:79], v[174:177], v[156:159], v[64:79]
	ds_read_b64_tr_b16 v[128:129], v133 offset:128
	ds_read_b64_tr_b16 v[130:131], v134 offset:128
	ds_read_b64_tr_b16 v[174:175], v135 offset:128
	ds_read_b64_tr_b16 v[176:177], v155 offset:128
	s_waitcnt lgkmcnt(2)
	v_mfma_f32_32x32x16_bf16 v[48:63], v[128:131], v[156:159], v[48:63]
	s_waitcnt lgkmcnt(0)
	v_mfma_f32_32x32x16_bf16 v[16:31], v[174:177], v[156:159], v[16:31]
	ds_read_b64_tr_b16 v[128:129], v133 offset:192
	ds_read_b64_tr_b16 v[130:131], v134 offset:192
	ds_read_b64_tr_b16 v[174:175], v135 offset:192
	ds_read_b64_tr_b16 v[176:177], v155 offset:192
	v_add_u32_e32 v133, 0x17000, v154
	v_add_u32_e32 v135, 0x21000, v154
	v_add_u32_e32 v155, 0x21500, v154
	v_add_u32_e32 v134, 0x17500, v154
	s_waitcnt lgkmcnt(2)
	v_mfma_f32_32x32x16_bf16 v[32:47], v[128:131], v[156:159], v[32:47]
	s_waitcnt lgkmcnt(0)
	v_mfma_f32_32x32x16_bf16 v[0:15], v[174:177], v[156:159], v[0:15]
	ds_read_b64_tr_b16 v[128:129], v133
	ds_read_b64_tr_b16 v[130:131], v134
	ds_read_b64_tr_b16 v[156:157], v132 offset:36864
	ds_read_b64_tr_b16 v[158:159], v132 offset:39168
	ds_read_b64_tr_b16 v[174:175], v135
	ds_read_b64_tr_b16 v[176:177], v155
	s_waitcnt lgkmcnt(2)
	v_mfma_f32_32x32x16_bf16 v[112:127], v[128:131], v[156:159], v[112:127]
	s_waitcnt lgkmcnt(0)
	v_mfma_f32_32x32x16_bf16 v[96:111], v[174:177], v[156:159], v[96:111]
	ds_read_b64_tr_b16 v[128:129], v133 offset:64
	ds_read_b64_tr_b16 v[130:131], v134 offset:64
	ds_read_b64_tr_b16 v[174:175], v135 offset:64
	ds_read_b64_tr_b16 v[176:177], v155 offset:64
	s_waitcnt lgkmcnt(2)
	v_mfma_f32_32x32x16_bf16 v[80:95], v[128:131], v[156:159], v[80:95]
	s_waitcnt lgkmcnt(0)
	v_mfma_f32_32x32x16_bf16 v[64:79], v[174:177], v[156:159], v[64:79]
	ds_read_b64_tr_b16 v[128:129], v133 offset:128
	ds_read_b64_tr_b16 v[130:131], v134 offset:128
	ds_read_b64_tr_b16 v[174:175], v135 offset:128
	ds_read_b64_tr_b16 v[176:177], v155 offset:128
	s_waitcnt lgkmcnt(2)
	v_mfma_f32_32x32x16_bf16 v[48:63], v[128:131], v[156:159], v[48:63]
	s_waitcnt lgkmcnt(0)
	v_mfma_f32_32x32x16_bf16 v[16:31], v[174:177], v[156:159], v[16:31]
	ds_read_b64_tr_b16 v[128:129], v133 offset:192
	ds_read_b64_tr_b16 v[130:131], v134 offset:192
	ds_read_b64_tr_b16 v[174:175], v135 offset:192
	ds_read_b64_tr_b16 v[176:177], v155 offset:192
	v_add_u32_e32 v133, 0x18400, v154
	v_add_u32_e32 v135, 0x22400, v154
	v_add_u32_e32 v155, 0x22900, v154
	v_add_u32_e32 v134, 0x18900, v154
	s_waitcnt lgkmcnt(2)
	v_mfma_f32_32x32x16_bf16 v[32:47], v[128:131], v[156:159], v[32:47]
	s_waitcnt lgkmcnt(0)
	v_mfma_f32_32x32x16_bf16 v[0:15], v[174:177], v[156:159], v[0:15]
	ds_read_b64_tr_b16 v[128:129], v133
	ds_read_b64_tr_b16 v[130:131], v134
	ds_read_b64_tr_b16 v[156:157], v132 offset:46080
	ds_read_b64_tr_b16 v[158:159], v132 offset:48384
	ds_read_b64_tr_b16 v[174:175], v135
	ds_read_b64_tr_b16 v[176:177], v155
	s_waitcnt lgkmcnt(2)
	v_mfma_f32_32x32x16_bf16 v[112:127], v[128:131], v[156:159], v[112:127]
	s_waitcnt lgkmcnt(0)
	v_mfma_f32_32x32x16_bf16 v[96:111], v[174:177], v[156:159], v[96:111]
	ds_read_b64_tr_b16 v[128:129], v133 offset:64
	ds_read_b64_tr_b16 v[130:131], v134 offset:64
	ds_read_b64_tr_b16 v[174:175], v135 offset:64
	ds_read_b64_tr_b16 v[176:177], v155 offset:64
	s_waitcnt lgkmcnt(2)
	v_mfma_f32_32x32x16_bf16 v[80:95], v[128:131], v[156:159], v[80:95]
	s_waitcnt lgkmcnt(0)
	v_mfma_f32_32x32x16_bf16 v[64:79], v[174:177], v[156:159], v[64:79]
	ds_read_b64_tr_b16 v[128:129], v133 offset:128
	ds_read_b64_tr_b16 v[130:131], v134 offset:128
	ds_read_b64_tr_b16 v[174:175], v135 offset:128
	ds_read_b64_tr_b16 v[176:177], v155 offset:128
	s_waitcnt lgkmcnt(2)
	v_mfma_f32_32x32x16_bf16 v[48:63], v[128:131], v[156:159], v[48:63]
	s_waitcnt lgkmcnt(0)
	v_mfma_f32_32x32x16_bf16 v[16:31], v[174:177], v[156:159], v[16:31]
	ds_read_b64_tr_b16 v[128:129], v133 offset:192
	ds_read_b64_tr_b16 v[130:131], v134 offset:192
	ds_read_b64_tr_b16 v[174:175], v135 offset:192
	ds_read_b64_tr_b16 v[176:177], v155 offset:192
	v_add_u32_e32 v133, 0x19800, v154
	v_add_u32_e32 v135, 0x23800, v154
	v_add_u32_e32 v155, 0x23d00, v154
	v_add_u32_e32 v134, 0x19d00, v154
	s_waitcnt lgkmcnt(2)
	v_mfma_f32_32x32x16_bf16 v[32:47], v[128:131], v[156:159], v[32:47]
	s_waitcnt lgkmcnt(0)
	v_mfma_f32_32x32x16_bf16 v[0:15], v[174:177], v[156:159], v[0:15]
	ds_read_b64_tr_b16 v[128:129], v133
	ds_read_b64_tr_b16 v[130:131], v134
	ds_read_b64_tr_b16 v[174:175], v132 offset:55296
	ds_read_b64_tr_b16 v[176:177], v132 offset:57600
	ds_read_b64_tr_b16 v[156:157], v135
	ds_read_b64_tr_b16 v[158:159], v155
	s_waitcnt lgkmcnt(2)
	v_mfma_f32_32x32x16_bf16 v[112:127], v[128:131], v[174:177], v[112:127]
	s_waitcnt lgkmcnt(0)
	v_mfma_f32_32x32x16_bf16 v[96:111], v[156:159], v[174:177], v[96:111]
	ds_read_b64_tr_b16 v[128:129], v133 offset:64
	ds_read_b64_tr_b16 v[130:131], v134 offset:64
	ds_read_b64_tr_b16 v[156:157], v135 offset:64
	ds_read_b64_tr_b16 v[158:159], v155 offset:64
	s_waitcnt lgkmcnt(2)
	v_mfma_f32_32x32x16_bf16 v[80:95], v[128:131], v[174:177], v[80:95]
	s_waitcnt lgkmcnt(0)
	v_mfma_f32_32x32x16_bf16 v[64:79], v[156:159], v[174:177], v[64:79]
	ds_read_b64_tr_b16 v[128:129], v133 offset:128
	ds_read_b64_tr_b16 v[130:131], v134 offset:128
	ds_read_b64_tr_b16 v[156:157], v135 offset:128
	ds_read_b64_tr_b16 v[158:159], v155 offset:128
	s_waitcnt lgkmcnt(2)
	v_mfma_f32_32x32x16_bf16 v[48:63], v[128:131], v[174:177], v[48:63]
	ds_read_b64_tr_b16 v[128:129], v133 offset:192
	ds_read_b64_tr_b16 v[130:131], v134 offset:192
	ds_read_b64_tr_b16 v[178:179], v135 offset:192
	ds_read_b64_tr_b16 v[180:181], v155 offset:192
	v_add_u32_e32 v134, 0x900, v132
	v_add_u32_e32 v155, 0x1b100, v154
	s_waitcnt lgkmcnt(4)
; __device__ __forceinline__ f32x16 mfma32(bf16x8 a, bf16x8 b, f32x16 c) { return __builtin_amdgcn_mfma_f32_32x32x16_bf16(a, b, c, 0, 0, 0); }
; __device__ void ret_state_item(const bf16_t* __restrict__ Kb, const bf16_t* __restrict__ Vb, bf16_t* __restrict__ STf, bf16_t* __restrict__ STb,
;                                int cidx, int head, float lgf2, float lgb2, LAS unsigned char* lds) {
;     ...
;   for (int ks = 0; ks < 8; ++ks) {
;     const unsigned r = (unsigned)(16 * ks + 8 * h + q4);
;     const bf16x8 Bv = tr_frag(lds, r * VS + w * 64 + cofs, (r + 4) * VS + w * 64 + cofs);
; #pragma unroll
;     for (int dt = 0; dt < 4; ++dt) {
;       const bf16x8 Af = tr_frag(lds, OKF + r * KS + dt * 64 + cofs, OKF + (r + 4) * KS + dt * 64 + cofs);
;       const bf16x8 Ab = tr_frag(lds, OKB + r * KS + dt * 64 + cofs, OKB + (r + 4) * KS + dt * 64 + cofs);
;       af[dt] = mfma32(Af, Bv, af[dt]); ab[dt] = mfma32(Ab, Bv, ab[dt]);
;     }
;   }
;   const size_t ob = ((size_t)(cidx * 4 + head) * 256 + w * 32 + (l & 31)) * 128;
; #pragma unroll
;   for (int dt = 0; dt < 4; ++dt) { store_tile16(STf + ob + dt * 32, af[dt], 1.f, h); store_tile16(STb + ob + dt * 32, ab[dt], 1.f, h); }
;   __syncthreads();
	v_mfma_f32_32x32x16_bf16 v[16:31], v[156:159], v[174:177], v[16:31]
	v_add_u32_e32 v156, 0x1ac00, v154
	v_add_u32_e32 v157, 0x24c00, v154
	v_add_u32_e32 v158, 0x25100, v154
	s_waitcnt lgkmcnt(2)
	v_mfma_f32_32x32x16_bf16 v[32:47], v[128:131], v[174:177], v[32:47]
	ds_read_b64_tr_b16 v[128:129], v156
	ds_read_b64_tr_b16 v[130:131], v155
	ds_read_b64_tr_b16 v[132:133], v132 offset:64512
	ds_read_b64_tr_b16 v[134:135], v134 offset:64512
	s_waitcnt lgkmcnt(4)
	v_mfma_f32_32x32x16_bf16 v[0:15], v[178:181], v[174:177], v[0:15]
	ds_read_b64_tr_b16 v[174:175], v157
	ds_read_b64_tr_b16 v[176:177], v158
	s_waitcnt lgkmcnt(2)
	v_mfma_f32_32x32x16_bf16 v[112:127], v[128:131], v[132:135], v[112:127]
	s_waitcnt lgkmcnt(0)
	v_mfma_f32_32x32x16_bf16 v[96:111], v[174:177], v[132:135], v[96:111]
	ds_read_b64_tr_b16 v[128:129], v156 offset:64
	ds_read_b64_tr_b16 v[130:131], v155 offset:64
	ds_read_b64_tr_b16 v[174:175], v157 offset:64
	ds_read_b64_tr_b16 v[176:177], v158 offset:64
	s_nop 5
	v_cvt_pk_bf16_f32 v112, v112, v113
	v_cvt_pk_bf16_f32 v113, v114, v115
	v_cvt_pk_bf16_f32 v114, v116, v117
	v_cvt_pk_bf16_f32 v115, v118, v119
	s_nop 0
	v_permlane32_swap_b32_e32 v112, v114
	s_waitcnt lgkmcnt(2)
	v_mfma_f32_32x32x16_bf16 v[80:95], v[128:131], v[132:135], v[80:95]
	v_cvt_pk_bf16_f32 v96, v96, v97
	v_cvt_pk_bf16_f32 v97, v98, v99
	v_cvt_pk_bf16_f32 v98, v100, v101
	v_cvt_pk_bf16_f32 v99, v102, v103
	v_permlane32_swap_b32_e32 v113, v115
	v_permlane32_swap_b32_e32 v96, v98
	s_waitcnt lgkmcnt(0)
	v_mfma_f32_32x32x16_bf16 v[64:79], v[174:177], v[132:135], v[64:79]
	ds_read_b64_tr_b16 v[128:129], v156 offset:128
	ds_read_b64_tr_b16 v[130:131], v155 offset:128
	ds_read_b64_tr_b16 v[174:175], v157 offset:128
	ds_read_b64_tr_b16 v[176:177], v158 offset:128
	v_cvt_pk_bf16_f32 v80, v80, v81
	v_cvt_pk_bf16_f32 v81, v82, v83
	v_cvt_pk_bf16_f32 v82, v84, v85
	v_cvt_pk_bf16_f32 v83, v86, v87
	v_permlane32_swap_b32_e32 v97, v99
	s_waitcnt lgkmcnt(2)
	v_mfma_f32_32x32x16_bf16 v[48:63], v[128:131], v[132:135], v[48:63]
	ds_read_b64_tr_b16 v[128:129], v156 offset:192
	ds_read_b64_tr_b16 v[130:131], v155 offset:192
	ds_read_b64_tr_b16 v[154:155], v157 offset:192
	ds_read_b64_tr_b16 v[156:157], v158 offset:192
	v_cvt_pk_bf16_f32 v64, v64, v65
	v_cvt_pk_bf16_f32 v65, v66, v67
	v_cvt_pk_bf16_f32 v66, v68, v69
	v_cvt_pk_bf16_f32 v67, v70, v71
	v_permlane32_swap_b32_e32 v80, v82
	s_waitcnt lgkmcnt(4)
	v_mfma_f32_32x32x16_bf16 v[16:31], v[174:177], v[132:135], v[16:31]
	s_nop 0
	v_cvt_pk_bf16_f32 v48, v48, v49
	v_cvt_pk_bf16_f32 v49, v50, v51
	v_cvt_pk_bf16_f32 v50, v52, v53
	v_cvt_pk_bf16_f32 v51, v54, v55
	v_permlane32_swap_b32_e32 v81, v83
	v_permlane32_swap_b32_e32 v64, v66
	s_waitcnt lgkmcnt(2)
	v_mfma_f32_32x32x16_bf16 v[32:47], v[128:131], v[132:135], v[32:47]
	v_ashrrev_i32_e32 v128, 1, v152
	v_and_b32_e32 v128, 0xffffffe0, v128
	v_ashrrev_i32_e32 v129, 31, v128
	v_or_b32_e32 v128, v128, v153
	v_lshl_add_u64 v[128:129], s[22:23], 0, v[128:129]
	v_lshlrev_b64 v[128:129], 8, v[128:129]
	v_lshl_add_u64 v[130:131], s[12:13], 0, v[128:129]
	s_waitcnt lgkmcnt(0)
	v_mfma_f32_32x32x16_bf16 v[0:15], v[154:157], v[132:135], v[0:15]
	v_readlane_b32 s12, v250, 53
	v_lshrrev_b32_e32 v132, 1, v152
	v_readlane_b32 s13, v250, 54
	v_and_b32_e32 v160, 16, v132
	v_cvt_pk_bf16_f32 v16, v16, v17
	v_lshl_add_u64 v[128:129], s[12:13], 0, v[128:129]
	v_cvt_pk_bf16_f32 v17, v18, v19
	v_cvt_pk_bf16_f32 v18, v20, v21
	v_cvt_pk_bf16_f32 v19, v22, v23
	v_lshl_add_u64 v[128:129], v[128:129], 0, v[160:161]
	v_permlane32_swap_b32_e32 v16, v18
	v_permlane32_swap_b32_e32 v17, v19
	global_store_dwordx4 v[128:129], v[16:19], off offset:128
	v_readlane_b32 s12, v255, 34
	v_cvt_pk_bf16_f32 v0, v0, v1
	v_cvt_pk_bf16_f32 v16, v24, v25
	v_cvt_pk_bf16_f32 v17, v26, v27
	v_cvt_pk_bf16_f32 v18, v28, v29
	v_cvt_pk_bf16_f32 v19, v30, v31
	s_nop 0
	v_permlane32_swap_b32_e32 v16, v18
	v_permlane32_swap_b32_e32 v17, v19
	global_store_dwordx4 v[128:129], v[16:19], off offset:160
	v_cvt_pk_bf16_f32 v1, v2, v3
	v_cvt_pk_bf16_f32 v2, v4, v5
	v_cvt_pk_bf16_f32 v16, v32, v33
	v_cvt_pk_bf16_f32 v17, v34, v35
	v_cvt_pk_bf16_f32 v18, v36, v37
	v_cvt_pk_bf16_f32 v19, v38, v39
	v_cvt_pk_bf16_f32 v3, v6, v7
	s_add_i32 s6, s6, s12
	v_readlane_b32 s12, v255, 40
	v_lshl_add_u64 v[130:131], v[130:131], 0, v[160:161]
	v_permlane32_swap_b32_e32 v65, v67
	v_permlane32_swap_b32_e32 v48, v50
	v_permlane32_swap_b32_e32 v49, v51
	v_permlane32_swap_b32_e32 v16, v18
	v_permlane32_swap_b32_e32 v17, v19
	v_permlane32_swap_b32_e32 v0, v2
	v_permlane32_swap_b32_e32 v1, v3
	v_readlane_b32 s13, v255, 41
	s_add_u32 s22, s22, s12
	global_store_dwordx4 v[130:131], v[112:115], off
	global_store_dwordx4 v[128:129], v[96:99], off
	global_store_dwordx4 v[130:131], v[80:83], off offset:64
	v_cvt_pk_bf16_f32 v112, v120, v121
	v_cvt_pk_bf16_f32 v113, v122, v123
	v_cvt_pk_bf16_f32 v114, v124, v125
	v_cvt_pk_bf16_f32 v115, v126, v127
	v_cvt_pk_bf16_f32 v96, v104, v105
	v_cvt_pk_bf16_f32 v97, v106, v107
	v_cvt_pk_bf16_f32 v98, v108, v109
	v_cvt_pk_bf16_f32 v99, v110, v111
	v_cvt_pk_bf16_f32 v80, v88, v89
	v_cvt_pk_bf16_f32 v81, v90, v91
	v_cvt_pk_bf16_f32 v82, v92, v93
	v_cvt_pk_bf16_f32 v83, v94, v95
	global_store_dwordx4 v[128:129], v[64:67], off offset:64
	global_store_dwordx4 v[130:131], v[48:51], off offset:128
	global_store_dwordx4 v[130:131], v[16:19], off offset:192
	v_cvt_pk_bf16_f32 v64, v72, v73
	v_cvt_pk_bf16_f32 v65, v74, v75
	v_cvt_pk_bf16_f32 v66, v76, v77
	v_cvt_pk_bf16_f32 v67, v78, v79
	v_cvt_pk_bf16_f32 v48, v56, v57
	v_cvt_pk_bf16_f32 v49, v58, v59
	v_cvt_pk_bf16_f32 v50, v60, v61
	v_cvt_pk_bf16_f32 v51, v62, v63
	v_cvt_pk_bf16_f32 v16, v40, v41
	v_cvt_pk_bf16_f32 v17, v42, v43
	v_cvt_pk_bf16_f32 v18, v44, v45
	v_cvt_pk_bf16_f32 v19, v46, v47
	global_store_dwordx4 v[128:129], v[0:3], off offset:192
	s_addc_u32 s23, s23, s13
	v_permlane32_swap_b32_e32 v112, v114
	v_cvt_pk_bf16_f32 v0, v8, v9
	v_cvt_pk_bf16_f32 v1, v10, v11
	v_cvt_pk_bf16_f32 v2, v12, v13
	v_cvt_pk_bf16_f32 v3, v14, v15
	v_permlane32_swap_b32_e32 v113, v115
	v_permlane32_swap_b32_e32 v96, v98
	v_permlane32_swap_b32_e32 v97, v99
	v_permlane32_swap_b32_e32 v80, v82
	v_permlane32_swap_b32_e32 v81, v83
	v_permlane32_swap_b32_e32 v64, v66
	v_permlane32_swap_b32_e32 v65, v67
	v_permlane32_swap_b32_e32 v48, v50
	v_permlane32_swap_b32_e32 v49, v51
	v_permlane32_swap_b32_e32 v16, v18
	v_permlane32_swap_b32_e32 v17, v19
	v_permlane32_swap_b32_e32 v0, v2
	v_permlane32_swap_b32_e32 v1, v3
	s_cmpk_gt_i32 s7, 0x3ff
	global_store_dwordx4 v[130:131], v[112:115], off offset:32
	global_store_dwordx4 v[128:129], v[96:99], off offset:32
	global_store_dwordx4 v[130:131], v[80:83], off offset:96
	global_store_dwordx4 v[128:129], v[64:67], off offset:96
	global_store_dwordx4 v[130:131], v[48:51], off offset:160
	global_store_dwordx4 v[130:131], v[16:19], off offset:224
	global_store_dwordx4 v[128:129], v[0:3], off offset:224
	s_barrier
	s_cbranch_scc1 .LBB0_429

; #define LAS __attribute__((address_space(3)))
; template <int STAGE>
; __device__ void dft_phase(const bf16_t* src, bf16_t* dst, const bf16_t* DT, LAS unsigned char* lds) {
;   for (int it = blockIdx.x; it < 2048; it += gridDim.x) {
;     if (it < 1024) dft_item<STAGE>(src, dst, DT + DT_C128, DT + DT_S128, 128, 7, 16384, it >> 3, it & 7, 16384, 128, 128, lds);
.LBB0_505:
	s_or_b64 exec, exec, s[22:23]
	s_mov_b32 s69, 0
	s_and_b64 vcc, exec, s[64:65]
	v_readlane_b32 s6, v255, 32
	v_readlane_b32 s7, v255, 35
	v_readlane_b32 s12, v255, 28
	s_mov_b32 s13, s2
	s_waitcnt lgkmcnt(0)
	s_barrier
	s_cbranch_vccz .LBB0_511

; template <int STAGE>
; __device__ void dft_item(const bf16_t* __restrict__ src, bf16_t* __restrict__ dst, const bf16_t* __restrict__ Ct, const bf16_t* __restrict__ St,
;                          int N, int lgN, int rowbase, int j, int chblk, int S, int N1, int N2, LAS unsigned char* lds) {
;     ...
;     const int q = tid + it * 512, n = q >> lgcpr, cq = q & (cpr - 1), part = cq >> (lgcpr - 1), cc = cq & ((cpr >> 1) - 1);
;     const int irow = STAGE == 1 ? rowbase + N2 * n + j : rowbase + j * N2 + n;
;     const u32x4 v = *(const u32x4*)(src + (size_t)irow * 1024 + part * 512 + chblk * CB + cc * 8);
;     *(LAS u32x4*)(lds + n * stride + (part * CB + cc * 8) * 2) = v;
;   }
;   __syncthreads();
;   const int kts = N >> 5, kt = w & (kts - 1), chsub = w >> (lgN - 5);
;   const int i16 = l & 15, q4 = i16 >> 2, p4 = i16 & 3, G1 = (l >> 4) & 1, h = l >> 5;
;   const unsigned colre = (unsigned)(chsub * 32 + 16 * G1 + 4 * p4) * 2u, colim = colre + (unsigned)CB * 2u;
;   const int kout = kt * 32 + (l & 31);
;   f32x16 a0 = {}, a1 = {}, a2 = {};
;   const int nks = N >> 4;
;   bf16x8 Bc[8], Bs[8];
; #pragma unroll
;   for (int ks = 0; ks < 8; ++ks) if (ks < nks) { Bc[ks] = *(const bf16x8*)(Ct + kout * N + 16 * ks + 8 * h); Bs[ks] = *(const bf16x8*)(St + kout * N + 16 * ks + 8 * h); }
; #pragma unroll
;   for (int ks = 0; ks < 8; ++ks) if (ks < nks) {
;     const unsigned rlo = (unsigned)(16 * ks + 8 * h + q4) * stride, rhi = rlo + 4u * stride;
;     const bf16x8 Ar = tr_frag(lds, rlo + colre, rhi + colre), Ai = tr_frag(lds, rlo + colim, rhi + colim);
;     a0 = mfma32(Ar, Bc[ks], a0); a0 = mfma32(Ai, Bs[ks], a0);
;     if (STAGE == 1) { a1 = mfma32(Ai, Bc[ks], a1); a2 = mfma32(Ar, Bs[ks], a2); }
;   }
;   const int chb = chblk * CB + chsub * 32;
;   if (STAGE == 1) {
;     const int mm = (j * kout) & (S - 1); const float fr = (float)mm / (float)S;
;     const float c = __builtin_amdgcn_cosf(fr), s = __builtin_amdgcn_sinf(fr);
;     const size_t orow = (size_t)(rowbase + kout * N2 + j) * 1024;
;     f32x16 re, im;
; #pragma unroll
;     for (int i = 0; i < 16; ++i) { const float yr = a0[i], yi = a1[i] - a2[i]; re[i] = yr * c + yi * s; im[i] = yi * c - yr * s; }
;     store_tile16(dst + orow + chb, re, 1.f, h); store_tile16(dst + orow + 512 + chb, im, 1.f, h);
;   } else {
;     const size_t orow = (size_t)(rowbase + j + N1 * kout) * 512;
.LBB0_511:
	s_cmpk_gt_i32 s13, 0x3ff
	s_mov_b64 s[22:23], -1
	s_cbranch_scc0 .LBB0_513
	v_mov_b32_e32 v20, v214
	s_and_b32 s23, s12, 0x7ffff800
	s_bfe_u32 s22, s13, 0x50002
	s_addk_i32 s23, 0xc000
	v_lshlrev_b32_e32 v2, 4, v20
	s_lshl_b32 s20, s22, 6
	v_and_b32_e32 v16, 0xf0, v2
	v_add_u32_e32 v2, 0x200, v20
	v_add_u32_e32 v8, 0x400, v20
	v_add_u32_e32 v10, 0x600, v20
	s_or_b32 s35, s20, s23
	v_ashrrev_i32_e32 v18, 5, v20
	v_ashrrev_i32_e32 v21, 5, v2
	v_ashrrev_i32_e32 v22, 5, v8
	v_ashrrev_i32_e32 v23, 5, v10
	v_add_u32_e32 v0, s35, v18
	v_add_u32_e32 v2, s35, v21
	v_add_u32_e32 v8, s35, v22
	v_add_u32_e32 v10, s35, v23
	v_ashrrev_i32_e32 v1, 31, v0
	v_ashrrev_i32_e32 v3, 31, v2
	v_ashrrev_i32_e32 v9, 31, v8
	v_ashrrev_i32_e32 v11, 31, v10
	v_bfe_u32 v19, v20, 4, 1
	v_lshlrev_b64 v[0:1], 11, v[0:1]
	v_lshlrev_b64 v[2:3], 11, v[2:3]
	v_lshlrev_b64 v[8:9], 11, v[8:9]
	v_lshlrev_b64 v[10:11], 11, v[10:11]
	s_and_b32 s34, s7, 0x180
	v_lshl_add_u64 v[0:1], s[10:11], 0, v[0:1]
	v_lshlrev_b32_e32 v160, 10, v19
	v_lshl_add_u64 v[2:3], s[10:11], 0, v[2:3]
	v_lshl_add_u64 v[8:9], s[10:11], 0, v[8:9]
	v_lshl_add_u64 v[10:11], s[10:11], 0, v[10:11]
	v_lshl_add_u64 v[0:1], v[0:1], 0, v[160:161]
	s_lshl_b32 s20, s34, 1
	v_lshl_add_u64 v[2:3], v[2:3], 0, v[160:161]
	v_lshl_add_u64 v[8:9], v[8:9], 0, v[160:161]
	v_lshl_add_u64 v[10:11], v[10:11], 0, v[160:161]
	v_lshl_add_u64 v[0:1], v[0:1], 0, s[20:21]
	v_mov_b32_e32 v17, v161
	v_lshl_add_u64 v[2:3], v[2:3], 0, s[20:21]
	v_lshl_add_u64 v[8:9], v[8:9], 0, s[20:21]
	v_lshl_add_u64 v[10:11], v[10:11], 0, s[20:21]
	v_lshl_add_u64 v[0:1], v[0:1], 0, v[16:17]
	v_lshl_add_u64 v[4:5], v[2:3], 0, v[16:17]
	v_lshl_add_u64 v[8:9], v[8:9], 0, v[16:17]
	v_lshl_add_u64 v[12:13], v[10:11], 0, v[16:17]
	global_load_dwordx4 v[0:3], v[0:1], off
	s_nop 0
	global_load_dwordx4 v[4:7], v[4:5], off
	s_nop 0
	global_load_dwordx4 v[8:11], v[8:9], off
	s_nop 0
	global_load_dwordx4 v[12:15], v[12:13], off
	v_and_b32_e32 v17, 31, v20
	v_lshrrev_b32_e32 v24, 1, v20
	v_mul_lo_u32 v18, v18, s54
	v_lshlrev_b32_e32 v19, 8, v19
	v_and_or_b32 v42, v24, 32, v17
	v_add_u32_e32 v17, 0, v18
	v_mul_lo_u32 v18, v21, s54
	v_mul_lo_u32 v21, v22, s54
	v_mul_lo_u32 v22, v23, s54
	v_readlane_b32 s36, v252, 41
	v_add3_u32 v23, v17, v19, v16
	v_add_u32_e32 v17, 0, v18
	v_add_u32_e32 v18, 0, v21
	v_add_u32_e32 v21, 0, v22
	v_lshlrev_b32_e32 v160, 7, v42
	v_readlane_b32 s37, v252, 42
	v_mov_b32_e32 v37, v161
	v_and_b32_e32 v36, 16, v24
	v_add3_u32 v22, v17, v19, v16
	v_add3_u32 v18, v18, v19, v16
	v_add3_u32 v19, v21, v19, v16
	v_lshl_add_u64 v[16:17], s[36:37], 0, v[160:161]
	v_lshl_add_u64 v[38:39], v[16:17], 0, v[36:37]
	v_readlane_b32 s36, v252, 43
	v_readlane_b32 s37, v252, 44
	s_cmp_eq_u32 s69, 2
	s_cbranch_scc1 .Ldtskip_2
	v_lshl_add_u64 v[210:211], s[36:37], 0, v[160:161]
	v_lshl_add_u64 v[40:41], v[210:211], 0, v[36:37]
	global_load_dwordx4 v[50:53], v[38:39], off
	global_load_dwordx4 v[54:57], v[40:41], off
	global_load_dwordx4 v[58:61], v[38:39], off offset:32
	global_load_dwordx4 v[62:65], v[40:41], off offset:32
	global_load_dwordx4 v[66:69], v[38:39], off offset:64
	global_load_dwordx4 v[70:73], v[40:41], off offset:64
	global_load_dwordx4 v[74:77], v[38:39], off offset:96
	global_load_dwordx4 v[78:81], v[40:41], off offset:96
	s_mov_b32 s69, 2
	s_waitcnt vmcnt(11)
	ds_write_b128 v23, v[0:3]
	s_waitcnt vmcnt(10)
	ds_write_b128 v22, v[4:7]
	s_waitcnt vmcnt(9)
	ds_write_b128 v18, v[8:11]
	s_waitcnt vmcnt(8)
	ds_write_b128 v19, v[12:15]
	s_branch .Ldtjoin_2
.Ldtskip_2:
	s_waitcnt vmcnt(3)
	ds_write_b128 v23, v[0:3]
	s_waitcnt vmcnt(2)
	ds_write_b128 v22, v[4:7]
	s_waitcnt vmcnt(1)
	ds_write_b128 v18, v[8:11]
	s_waitcnt vmcnt(0)
	ds_write_b128 v19, v[12:15]
.Ldtjoin_2:
	s_waitcnt lgkmcnt(0)
	s_barrier
	v_lshrrev_b32_e32 v4, 2, v20
	v_and_b32_e32 v5, 16, v20
	v_ashrrev_i32_e32 v6, 2, v20
	v_lshlrev_b32_e32 v7, 2, v20
	v_and_b32_e32 v43, 0xffffffe0, v6
	v_and_b32_e32 v6, 12, v7
	v_and_b32_e32 v4, 11, v4
	v_or3_b32 v5, v5, v6, v43
	v_mul_u32_u24_e32 v4, 0x240, v4
	v_lshlrev_b32_e32 v5, 1, v5
	v_add3_u32 v44, 0, v5, v4
	ds_read_b64_tr_b16 v[4:5], v44
	ds_read_b64_tr_b16 v[6:7], v44 offset:2304
	ds_read_b64_tr_b16 v[30:31], v44 offset:2560
	ds_read_b64_tr_b16 v[28:29], v44 offset:256
	s_waitcnt vmcnt(7) lgkmcnt(2)
	v_mfma_f32_32x32x16_bf16 v[0:15], v[4:7], v[50:53], 0
	s_waitcnt vmcnt(6) lgkmcnt(0)
	v_mfma_f32_32x32x16_bf16 v[0:15], v[28:31], v[54:57], v[0:15]
	ds_read_b64_tr_b16 v[16:17], v44 offset:9216
	ds_read_b64_tr_b16 v[18:19], v44 offset:11520
	ds_read_b64_tr_b16 v[30:31], v44 offset:11776
	ds_read_b64_tr_b16 v[28:29], v44 offset:9472
	s_waitcnt vmcnt(5) lgkmcnt(2)
	v_mfma_f32_32x32x16_bf16 v[0:15], v[16:19], v[58:61], v[0:15]
	ds_read_b64_tr_b16 v[20:21], v44 offset:18432
	ds_read_b64_tr_b16 v[22:23], v44 offset:20736
	s_waitcnt vmcnt(4) lgkmcnt(2)
	v_mfma_f32_32x32x16_bf16 v[0:15], v[28:31], v[62:65], v[0:15]
	ds_read_b64_tr_b16 v[30:31], v44 offset:20992
	ds_read_b64_tr_b16 v[28:29], v44 offset:18688
	s_waitcnt vmcnt(3) lgkmcnt(2)
	v_mfma_f32_32x32x16_bf16 v[0:15], v[20:23], v[66:69], v[0:15]
	v_add_u32_e32 v32, s34, v43
	v_ashrrev_i32_e32 v33, 31, v32
	s_waitcnt vmcnt(2) lgkmcnt(0)
	v_mfma_f32_32x32x16_bf16 v[0:15], v[28:31], v[70:73], v[0:15]
	ds_read_b64_tr_b16 v[16:17], v44 offset:27648
	ds_read_b64_tr_b16 v[18:19], v44 offset:29952
	ds_read_b64_tr_b16 v[30:31], v44 offset:30208
	ds_read_b64_tr_b16 v[28:29], v44 offset:27904
	s_waitcnt vmcnt(1) lgkmcnt(2)
	v_mfma_f32_32x32x16_bf16 v[0:15], v[16:19], v[74:77], v[0:15]
	v_lshl_or_b32 v16, v42, 5, s23
	v_or_b32_e32 v160, s22, v16
	v_readlane_b32 s22, v253, 3
	v_lshlrev_b64 v[16:17], 10, v[160:161]
	v_readlane_b32 s23, v253, 4
	s_waitcnt vmcnt(0) lgkmcnt(0)
	v_mfma_f32_32x32x16_bf16 v[0:15], v[28:31], v[78:81], v[0:15]
	v_lshl_add_u64 v[16:17], s[22:23], 0, v[16:17]
	v_lshl_add_u64 v[16:17], v[32:33], 1, v[16:17]
	v_lshl_add_u64 v[16:17], v[16:17], 0, v[36:37]
	s_mov_b64 s[22:23], 0
	s_nop 7
	v_cvt_pk_bf16_f32 v0, v0, v1
	v_cvt_pk_bf16_f32 v1, v2, v3
	v_cvt_pk_bf16_f32 v2, v4, v5
	v_cvt_pk_bf16_f32 v3, v6, v7
	v_cvt_pk_bf16_f32 v4, v8, v9
	v_cvt_pk_bf16_f32 v5, v10, v11
	v_cvt_pk_bf16_f32 v6, v12, v13
	v_cvt_pk_bf16_f32 v7, v14, v15
	v_permlane32_swap_b32_e32 v0, v2
	v_permlane32_swap_b32_e32 v1, v3
	v_permlane32_swap_b32_e32 v4, v6
	v_permlane32_swap_b32_e32 v5, v7
	global_store_dwordx4 v[16:17], v[0:3], off
	global_store_dwordx4 v[16:17], v[4:7], off offset:32
	s_barrier
; #define LAS __attribute__((address_space(3)))
; template <int STAGE>
; __device__ void dft_item(const bf16_t* __restrict__ src, bf16_t* __restrict__ dst, const bf16_t* __restrict__ Ct, const bf16_t* __restrict__ St,
;                          int N, int lgN, int rowbase, int j, int chblk, int S, int N1, int N2, LAS unsigned char* lds) {
;     ...
;     const int q = tid + it * 512, n = q >> lgcpr, cq = q & (cpr - 1), part = cq >> (lgcpr - 1), cc = cq & ((cpr >> 1) - 1);
;     const int irow = STAGE == 1 ? rowbase + N2 * n + j : rowbase + j * N2 + n;
;     const u32x4 v = *(const u32x4*)(src + (size_t)irow * 1024 + part * 512 + chblk * CB + cc * 8);
;     *(LAS u32x4*)(lds + n * stride + (part * CB + cc * 8) * 2) = v;
;   }
;   __syncthreads();
;   const int kts = N >> 5, kt = w & (kts - 1), chsub = w >> (lgN - 5);
;   const int i16 = l & 15, q4 = i16 >> 2, p4 = i16 & 3, G1 = (l >> 4) & 1, h = l >> 5;
;   const unsigned colre = (unsigned)(chsub * 32 + 16 * G1 + 4 * p4) * 2u, colim = colre + (unsigned)CB * 2u;
;   const int kout = kt * 32 + (l & 31);
;   f32x16 a0 = {}, a1 = {}, a2 = {};
;   const int nks = N >> 4;
;   bf16x8 Bc[8], Bs[8];
; #pragma unroll
;   for (int ks = 0; ks < 8; ++ks) if (ks < nks) { Bc[ks] = *(const bf16x8*)(Ct + kout * N + 16 * ks + 8 * h); Bs[ks] = *(const bf16x8*)(St + kout * N + 16 * ks + 8 * h); }
; #pragma unroll
;   for (int ks = 0; ks < 8; ++ks) if (ks < nks) {
;     const unsigned rlo = (unsigned)(16 * ks + 8 * h + q4) * stride, rhi = rlo + 4u * stride;
;     const bf16x8 Ar = tr_frag(lds, rlo + colre, rhi + colre), Ai = tr_frag(lds, rlo + colim, rhi + colim);
.LBB0_513:
	s_andn2_b64 vcc, exec, s[22:23]
	s_cbranch_vccnz .LBB0_510
	v_mov_b32_e32 v22, v214
	s_ashr_i32 s22, s13, 3
	s_lshl_b32 s20, s22, 7
	v_lshlrev_b32_e32 v2, 4, v22
	v_and_b32_e32 v18, 0x70, v2
	v_add_u32_e32 v2, 0x200, v22
	v_add_u32_e32 v8, 0x400, v22
	v_add_u32_e32 v10, 0x600, v22
	s_add_i32 s34, s20, 0x4000
	v_ashrrev_i32_e32 v16, 4, v22
	v_ashrrev_i32_e32 v21, 4, v2
	v_ashrrev_i32_e32 v23, 4, v8
	v_ashrrev_i32_e32 v24, 4, v10
	v_add_u32_e32 v0, s34, v16
	v_add_u32_e32 v2, s34, v21
	v_add_u32_e32 v8, s34, v23
	v_add_u32_e32 v10, s34, v24
	v_ashrrev_i32_e32 v1, 31, v0
	v_ashrrev_i32_e32 v3, 31, v2
	v_ashrrev_i32_e32 v9, 31, v8
	v_ashrrev_i32_e32 v11, 31, v10
	v_bfe_u32 v20, v22, 3, 1
	v_lshlrev_b64 v[0:1], 11, v[0:1]
	v_lshlrev_b64 v[2:3], 11, v[2:3]
	v_lshlrev_b64 v[8:9], 11, v[8:9]
	v_lshlrev_b64 v[10:11], 11, v[10:11]
	s_and_b32 s23, s6, 0x1c0
	v_lshl_add_u64 v[0:1], s[10:11], 0, v[0:1]
	v_lshlrev_b32_e32 v160, 10, v20
	v_lshl_add_u64 v[2:3], s[10:11], 0, v[2:3]
	v_lshl_add_u64 v[8:9], s[10:11], 0, v[8:9]
	v_lshl_add_u64 v[10:11], s[10:11], 0, v[10:11]
	v_lshl_add_u64 v[0:1], v[0:1], 0, v[160:161]
	s_lshl_b32 s20, s23, 1
	v_lshl_add_u64 v[2:3], v[2:3], 0, v[160:161]
	v_lshl_add_u64 v[8:9], v[8:9], 0, v[160:161]
	v_lshl_add_u64 v[10:11], v[10:11], 0, v[160:161]
	v_lshl_add_u64 v[0:1], v[0:1], 0, s[20:21]
	v_mov_b32_e32 v19, v161
	v_lshl_add_u64 v[2:3], v[2:3], 0, s[20:21]
	v_lshl_add_u64 v[8:9], v[8:9], 0, s[20:21]
	v_lshl_add_u64 v[10:11], v[10:11], 0, s[20:21]
	v_lshl_add_u64 v[0:1], v[0:1], 0, v[18:19]
	v_lshl_add_u64 v[4:5], v[2:3], 0, v[18:19]
	v_lshl_add_u64 v[8:9], v[8:9], 0, v[18:19]
	v_lshl_add_u64 v[12:13], v[10:11], 0, v[18:19]
	global_load_dwordx4 v[0:3], v[0:1], off
	s_nop 0
	global_load_dwordx4 v[4:7], v[4:5], off
	s_nop 0
	global_load_dwordx4 v[8:11], v[8:9], off
	s_nop 0
	global_load_dwordx4 v[12:15], v[12:13], off
	s_movk_i32 s20, 0x140
	v_lshrrev_b32_e32 v19, 1, v22
	v_and_b32_e32 v25, 31, v22
	v_mul_lo_u32 v26, v16, s20
	v_lshlrev_b32_e32 v20, 7, v20
	v_and_or_b32 v46, v19, s77, v25
	v_and_b32_e32 v16, 16, v19
	v_add_u32_e32 v19, 0, v26
	v_mul_lo_u32 v21, v21, s20
	v_mul_lo_u32 v23, v23, s20
	v_mul_lo_u32 v24, v24, s20
	v_readlane_b32 s34, v250, 49
	v_add3_u32 v25, v19, v20, v18
	v_add_u32_e32 v19, 0, v21
	v_add_u32_e32 v21, 0, v23
	v_add_u32_e32 v23, 0, v24
	v_lshlrev_b32_e32 v160, 8, v46
	v_readlane_b32 s35, v250, 50
	v_mov_b32_e32 v17, v161
	v_add3_u32 v24, v19, v20, v18
	v_add3_u32 v21, v21, v20, v18
	v_add3_u32 v20, v23, v20, v18
	v_lshl_add_u64 v[18:19], s[34:35], 0, v[160:161]
	v_lshl_add_u64 v[42:43], v[18:19], 0, v[16:17]
	v_readlane_b32 s34, v252, 37
	v_readlane_b32 s35, v252, 38
	s_addk_i32 s22, 0x4000
	s_cmp_eq_u32 s69, 1
	s_cbranch_scc1 .Ldtskip_1
	v_lshl_add_u64 v[210:211], s[34:35], 0, v[160:161]
	v_lshl_add_u64 v[44:45], v[210:211], 0, v[16:17]
	global_load_dwordx4 v[50:53], v[42:43], off
	global_load_dwordx4 v[54:57], v[44:45], off
	global_load_dwordx4 v[58:61], v[42:43], off offset:32
	global_load_dwordx4 v[62:65], v[44:45], off offset:32
	global_load_dwordx4 v[66:69], v[42:43], off offset:64
	global_load_dwordx4 v[70:73], v[44:45], off offset:64
	global_load_dwordx4 v[74:77], v[42:43], off offset:96
	global_load_dwordx4 v[78:81], v[44:45], off offset:96
	global_load_dwordx4 v[82:85], v[42:43], off offset:128
	global_load_dwordx4 v[86:89], v[44:45], off offset:128
	global_load_dwordx4 v[90:93], v[42:43], off offset:160
	global_load_dwordx4 v[94:97], v[44:45], off offset:160
	global_load_dwordx4 v[98:101], v[42:43], off offset:192
	global_load_dwordx4 v[102:105], v[44:45], off offset:192
	global_load_dwordx4 v[106:109], v[42:43], off offset:224
	global_load_dwordx4 v[110:113], v[44:45], off offset:224
	s_mov_b32 s69, 1
	s_waitcnt vmcnt(19)
	ds_write_b128 v25, v[0:3]
	s_waitcnt vmcnt(18)
	ds_write_b128 v24, v[4:7]
	s_waitcnt vmcnt(17)
	ds_write_b128 v21, v[8:11]
	s_waitcnt vmcnt(16)
	ds_write_b128 v20, v[12:15]
	s_branch .Ldtjoin_1
.Ldtskip_1:
	s_waitcnt vmcnt(3)
	ds_write_b128 v25, v[0:3]
	s_waitcnt vmcnt(2)
	ds_write_b128 v24, v[4:7]
	s_waitcnt vmcnt(1)
	ds_write_b128 v21, v[8:11]
	s_waitcnt vmcnt(0)
	ds_write_b128 v20, v[12:15]
; __device__ __forceinline__ f32x16 mfma32(bf16x8 a, bf16x8 b, f32x16 c) { return __builtin_amdgcn_mfma_f32_32x32x16_bf16(a, b, c, 0, 0, 0); }
; template <int STAGE>
; __device__ void dft_item(const bf16_t* __restrict__ src, bf16_t* __restrict__ dst, const bf16_t* __restrict__ Ct, const bf16_t* __restrict__ St,
;                          int N, int lgN, int rowbase, int j, int chblk, int S, int N1, int N2, LAS unsigned char* lds) {
;     ...
;   const int kts = N >> 5, kt = w & (kts - 1), chsub = w >> (lgN - 5);
;   const int i16 = l & 15, q4 = i16 >> 2, p4 = i16 & 3, G1 = (l >> 4) & 1, h = l >> 5;
;   const unsigned colre = (unsigned)(chsub * 32 + 16 * G1 + 4 * p4) * 2u, colim = colre + (unsigned)CB * 2u;
;   const int kout = kt * 32 + (l & 31);
;   f32x16 a0 = {}, a1 = {}, a2 = {};
;   const int nks = N >> 4;
;   bf16x8 Bc[8], Bs[8];
; #pragma unroll
;   for (int ks = 0; ks < 8; ++ks) if (ks < nks) { Bc[ks] = *(const bf16x8*)(Ct + kout * N + 16 * ks + 8 * h); Bs[ks] = *(const bf16x8*)(St + kout * N + 16 * ks + 8 * h); }
; #pragma unroll
;   for (int ks = 0; ks < 8; ++ks) if (ks < nks) {
;     const unsigned rlo = (unsigned)(16 * ks + 8 * h + q4) * stride, rhi = rlo + 4u * stride;
;     const bf16x8 Ar = tr_frag(lds, rlo + colre, rhi + colre), Ai = tr_frag(lds, rlo + colim, rhi + colim);
;     a0 = mfma32(Ar, Bc[ks], a0); a0 = mfma32(Ai, Bs[ks], a0);
;     if (STAGE == 1) { a1 = mfma32(Ai, Bc[ks], a1); a2 = mfma32(Ar, Bs[ks], a2); }
;   }
;   const int chb = chblk * CB + chsub * 32;
;   if (STAGE == 1) {
;     const int mm = (j * kout) & (S - 1); const float fr = (float)mm / (float)S;
;     const float c = __builtin_amdgcn_cosf(fr), s = __builtin_amdgcn_sinf(fr);
;     const size_t orow = (size_t)(rowbase + kout * N2 + j) * 1024;
;     f32x16 re, im;
; #pragma unroll
;     for (int i = 0; i < 16; ++i) { const float yr = a0[i], yi = a1[i] - a2[i]; re[i] = yr * c + yi * s; im[i] = yi * c - yr * s; }
;     store_tile16(dst + orow + chb, re, 1.f, h); store_tile16(dst + orow + 512 + chb, im, 1.f, h);
;   } else {
;     const size_t orow = (size_t)(rowbase + j + N1 * kout) * 512;
;     store_tile16(dst + orow + chb, a0, 1.f, h);
;   }
.Ldtjoin_1:
	s_waitcnt lgkmcnt(0)
	s_barrier
	v_lshrrev_b32_e32 v4, 2, v22
	v_and_b32_e32 v5, 16, v22
	v_ashrrev_i32_e32 v6, 3, v22
	v_lshlrev_b32_e32 v7, 2, v22
	v_and_b32_e32 v47, 0xffffffe0, v6
	v_and_b32_e32 v6, 12, v7
	v_and_b32_e32 v4, 11, v4
	v_or3_b32 v5, v5, v6, v47
	v_mul_u32_u24_e32 v4, 0x140, v4
	v_lshlrev_b32_e32 v5, 1, v5
	v_add3_u32 v48, 0, v5, v4
	ds_read_b64_tr_b16 v[4:5], v48
	ds_read_b64_tr_b16 v[6:7], v48 offset:1280
	ds_read_b64_tr_b16 v[32:33], v48 offset:1408
	ds_read_b64_tr_b16 v[30:31], v48 offset:128
	s_waitcnt vmcnt(15) lgkmcnt(2)
	v_mfma_f32_32x32x16_bf16 v[0:15], v[4:7], v[50:53], 0
	s_waitcnt vmcnt(14) lgkmcnt(0)
	v_mfma_f32_32x32x16_bf16 v[0:15], v[30:33], v[54:57], v[0:15]
	ds_read_b64_tr_b16 v[18:19], v48 offset:5120
	ds_read_b64_tr_b16 v[20:21], v48 offset:6400
	ds_read_b64_tr_b16 v[32:33], v48 offset:6528
	ds_read_b64_tr_b16 v[30:31], v48 offset:5248
	s_waitcnt vmcnt(13) lgkmcnt(2)
	v_mfma_f32_32x32x16_bf16 v[0:15], v[18:21], v[58:61], v[0:15]
	ds_read_b64_tr_b16 v[22:23], v48 offset:10240
	ds_read_b64_tr_b16 v[24:25], v48 offset:11520
	s_waitcnt vmcnt(12) lgkmcnt(2)
	v_mfma_f32_32x32x16_bf16 v[0:15], v[30:33], v[62:65], v[0:15]
	ds_read_b64_tr_b16 v[32:33], v48 offset:11648
	ds_read_b64_tr_b16 v[30:31], v48 offset:10368
	s_waitcnt vmcnt(11) lgkmcnt(2)
	v_mfma_f32_32x32x16_bf16 v[0:15], v[22:25], v[66:69], v[0:15]
	s_waitcnt vmcnt(10) lgkmcnt(0)
	v_mfma_f32_32x32x16_bf16 v[0:15], v[30:33], v[70:73], v[0:15]
	ds_read_b64_tr_b16 v[30:31], v48 offset:15360
	ds_read_b64_tr_b16 v[32:33], v48 offset:16640
	ds_read_b64_tr_b16 v[40:41], v48 offset:16768
	ds_read_b64_tr_b16 v[38:39], v48 offset:15488
	s_waitcnt vmcnt(9) lgkmcnt(2)
	v_mfma_f32_32x32x16_bf16 v[0:15], v[30:33], v[74:77], v[0:15]
	ds_read_b64_tr_b16 v[30:31], v48 offset:20480
	ds_read_b64_tr_b16 v[32:33], v48 offset:21760
	s_waitcnt vmcnt(8) lgkmcnt(2)
	v_mfma_f32_32x32x16_bf16 v[0:15], v[38:41], v[78:81], v[0:15]
	ds_read_b64_tr_b16 v[40:41], v48 offset:21888
	ds_read_b64_tr_b16 v[38:39], v48 offset:20608
	s_waitcnt vmcnt(7) lgkmcnt(2)
	v_mfma_f32_32x32x16_bf16 v[0:15], v[30:33], v[82:85], v[0:15]
	s_waitcnt vmcnt(6) lgkmcnt(0)
	v_mfma_f32_32x32x16_bf16 v[0:15], v[38:41], v[86:89], v[0:15]
	ds_read_b64_tr_b16 v[30:31], v48 offset:25600
	ds_read_b64_tr_b16 v[32:33], v48 offset:26880
	ds_read_b64_tr_b16 v[36:37], v48 offset:27008
	ds_read_b64_tr_b16 v[34:35], v48 offset:25728
	s_waitcnt vmcnt(5) lgkmcnt(2)
	v_mfma_f32_32x32x16_bf16 v[0:15], v[30:33], v[90:93], v[0:15]
	ds_read_b64_tr_b16 v[30:31], v48 offset:30720
	ds_read_b64_tr_b16 v[32:33], v48 offset:32000
	s_waitcnt vmcnt(4) lgkmcnt(2)
	v_mfma_f32_32x32x16_bf16 v[0:15], v[34:37], v[94:97], v[0:15]
	ds_read_b64_tr_b16 v[36:37], v48 offset:32128
	ds_read_b64_tr_b16 v[34:35], v48 offset:30848
	s_waitcnt vmcnt(3) lgkmcnt(2)
	v_mfma_f32_32x32x16_bf16 v[0:15], v[30:33], v[98:101], v[0:15]
	s_waitcnt vmcnt(2) lgkmcnt(0)
	v_mfma_f32_32x32x16_bf16 v[0:15], v[34:37], v[102:105], v[0:15]
	ds_read_b64_tr_b16 v[18:19], v48 offset:35840
	ds_read_b64_tr_b16 v[20:21], v48 offset:37120
	ds_read_b64_tr_b16 v[32:33], v48 offset:37248
	ds_read_b64_tr_b16 v[30:31], v48 offset:35968
	v_add_u32_e32 v34, s23, v47
	v_ashrrev_i32_e32 v35, 31, v34
	s_waitcnt vmcnt(1) lgkmcnt(2)
	v_mfma_f32_32x32x16_bf16 v[0:15], v[18:21], v[106:109], v[0:15]
	v_lshl_add_u32 v18, v46, 7, s22
	v_ashrrev_i32_e32 v19, 31, v18
	v_readlane_b32 s22, v253, 3
	v_lshlrev_b64 v[18:19], 10, v[18:19]
	v_readlane_b32 s23, v253, 4
	s_waitcnt vmcnt(0) lgkmcnt(0)
	v_mfma_f32_32x32x16_bf16 v[0:15], v[30:33], v[110:113], v[0:15]
	v_lshl_add_u64 v[18:19], s[22:23], 0, v[18:19]
	v_lshl_add_u64 v[18:19], v[34:35], 1, v[18:19]
	v_lshl_add_u64 v[16:17], v[18:19], 0, v[16:17]
	s_nop 8
	v_cvt_pk_bf16_f32 v0, v0, v1
	v_cvt_pk_bf16_f32 v1, v2, v3
	v_cvt_pk_bf16_f32 v2, v4, v5
	v_cvt_pk_bf16_f32 v3, v6, v7
	v_cvt_pk_bf16_f32 v4, v8, v9
	v_cvt_pk_bf16_f32 v5, v10, v11
	v_cvt_pk_bf16_f32 v6, v12, v13
	v_cvt_pk_bf16_f32 v7, v14, v15
	v_permlane32_swap_b32_e32 v0, v2
	v_permlane32_swap_b32_e32 v1, v3
	v_permlane32_swap_b32_e32 v4, v6
	v_permlane32_swap_b32_e32 v5, v7
	global_store_dwordx4 v[16:17], v[0:3], off
	global_store_dwordx4 v[16:17], v[4:7], off offset:32
	s_barrier
	s_branch .LBB0_510
